# MFMA issue order inside each 8-group changed so only one of srcA/srcB changes between neighbours (operand reuse), on top of v36
# speedup vs baseline: 1.0138x; 1.0138x over previous
.Lpeela:
	ds_read_b128 v[130:133], v208
	ds_read_b128 v[134:137], v208 offset:1024
	ds_read_b128 v[138:141], v208 offset:2048
	ds_read_b128 v[142:145], v208 offset:3072
	ds_read_b128 v[146:149], v209
	ds_read_b128 v[150:153], v209 offset:1024
	ds_read_b128 v[154:157], v209 offset:2048
	ds_read_b128 v[158:161], v209 offset:3072
	s_add_u32 s52, s50, 0xfff00080
	s_addc_u32 s53, s51, -1
	s_cmp_eq_u32 s89, 60
	s_cselect_b32 s55, s43, s53
	s_cselect_b32 s54, s85, s52
	s_cselect_b32 s53, s41, s88
	s_cselect_b32 s52, s86, s87
	v_lshl_add_u64 v[204:205], s[50:51], 0, v[192:193]
	s_add_i32 m0, s56, 0xc000
	ds_read_b128 v[162:165], v210
	ds_read_b128 v[166:169], v210 offset:1024
	ds_read_b128 v[170:173], v210 offset:2048
	ds_read_b128 v[174:177], v210 offset:3072
	ds_read_b128 v[200:203], v210 offset:4096
	ds_read_b128 v[212:215], v210 offset:5120
	ds_read_b128 v[216:219], v210 offset:6144
	ds_read_b128 v[224:227], v210 offset:7168
	global_load_lds_dwordx4 v[204:205], off
	v_lshl_add_u64 v[204:205], s[50:51], 0, v[194:195]
	s_add_i32 m0, s56, 0xe000
	s_nop 0
	global_load_lds_dwordx4 v[204:205], off
	s_waitcnt vmcnt(8)
	s_waitcnt lgkmcnt(0)
	s_setprio 1
	s_barrier
	v_mfma_f32_16x16x32_bf16 v[126:129], v[130:133], v[162:165], 0
	v_mfma_f32_16x16x32_bf16 v[122:125], v[138:141], v[162:165], 0
	v_mfma_f32_16x16x32_bf16 v[106:109], v[138:141], v[170:173], 0
	v_mfma_f32_16x16x32_bf16 v[110:113], v[130:133], v[170:173], 0
	v_mfma_f32_16x16x32_bf16 v[94:97], v[130:133], v[200:203], 0
	v_mfma_f32_16x16x32_bf16 v[90:93], v[138:141], v[200:203], 0
	v_mfma_f32_16x16x32_bf16 v[74:77], v[138:141], v[216:219], 0
	v_mfma_f32_16x16x32_bf16 v[78:81], v[130:133], v[216:219], 0
	v_mfma_f32_16x16x32_bf16 v[126:129], v[134:137], v[166:169], v[126:129]
	v_mfma_f32_16x16x32_bf16 v[122:125], v[142:145], v[166:169], v[122:125]
	v_mfma_f32_16x16x32_bf16 v[106:109], v[142:145], v[174:177], v[106:109]
	v_mfma_f32_16x16x32_bf16 v[110:113], v[134:137], v[174:177], v[110:113]
	v_mfma_f32_16x16x32_bf16 v[94:97], v[134:137], v[212:215], v[94:97]
	v_mfma_f32_16x16x32_bf16 v[90:93], v[142:145], v[212:215], v[90:93]
	v_mfma_f32_16x16x32_bf16 v[74:77], v[142:145], v[224:227], v[74:77]
	v_mfma_f32_16x16x32_bf16 v[78:81], v[134:137], v[224:227], v[78:81]
	v_mfma_f32_16x16x32_bf16 v[118:121], v[146:149], v[162:165], 0
	v_mfma_f32_16x16x32_bf16 v[114:117], v[154:157], v[162:165], 0
	v_mfma_f32_16x16x32_bf16 v[98:101], v[154:157], v[170:173], 0
	v_mfma_f32_16x16x32_bf16 v[102:105], v[146:149], v[170:173], 0
	v_mfma_f32_16x16x32_bf16 v[86:89], v[146:149], v[200:203], 0
	v_mfma_f32_16x16x32_bf16 v[82:85], v[154:157], v[200:203], 0
	v_mfma_f32_16x16x32_bf16 v[66:69], v[154:157], v[216:219], 0
	v_mfma_f32_16x16x32_bf16 v[70:73], v[146:149], v[216:219], 0
	v_mfma_f32_16x16x32_bf16 v[118:121], v[150:153], v[166:169], v[118:121]
	v_mfma_f32_16x16x32_bf16 v[114:117], v[158:161], v[166:169], v[114:117]
	v_mfma_f32_16x16x32_bf16 v[98:101], v[158:161], v[174:177], v[98:101]
	v_mfma_f32_16x16x32_bf16 v[102:105], v[150:153], v[174:177], v[102:105]
	v_mfma_f32_16x16x32_bf16 v[86:89], v[150:153], v[212:215], v[86:89]
	v_mfma_f32_16x16x32_bf16 v[82:85], v[158:161], v[212:215], v[82:85]
	v_mfma_f32_16x16x32_bf16 v[66:69], v[158:161], v[224:227], v[66:69]
	v_mfma_f32_16x16x32_bf16 v[70:73], v[150:153], v[224:227], v[70:73]
	s_barrier
	s_setprio 0
	s_add_i32 s90, s65, s31
	v_lshl_add_u64 v[204:205], s[52:53], 0, v[182:183]
	s_mov_b32 m0, s90
	ds_read_b128 v[162:165], v210 offset:16384
	ds_read_b128 v[166:169], v210 offset:17408
	ds_read_b128 v[170:173], v210 offset:18432
	ds_read_b128 v[174:177], v210 offset:19456
	ds_read_b128 v[200:203], v210 offset:20480
	ds_read_b128 v[212:215], v210 offset:21504
	ds_read_b128 v[216:219], v210 offset:22528
	ds_read_b128 v[224:227], v210 offset:23552
	global_load_lds_dwordx4 v[204:205], off
	s_add_i32 m0, s90, 0x2000
	s_add_u32 s90, s52, 0x100000
	v_lshl_add_u64 v[220:221], s[52:53], 0, v[178:179]
	s_addc_u32 s91, s53, 0
	s_add_i32 s92, s66, s31
	global_load_lds_dwordx4 v[220:221], off
	v_lshl_add_u64 v[228:229], s[90:91], 0, v[182:183]
	s_mov_b32 m0, s92
	v_lshl_add_u64 v[230:231], s[54:55], 0, v[180:181]
	global_load_lds_dwordx4 v[228:229], off
	v_lshl_add_u64 v[228:229], s[90:91], 0, v[178:179]
	s_add_i32 m0, s92, 0x2000
	s_nop 0
	global_load_lds_dwordx4 v[228:229], off
	v_lshl_add_u64 v[228:229], s[54:55], 0, v[184:185]
	s_mov_b32 m0, s56
	s_nop 0
	global_load_lds_dwordx4 v[228:229], off
	s_mov_b32 m0, s57
	s_nop 0
	global_load_lds_dwordx4 v[230:231], off
	s_waitcnt vmcnt(8)
	s_waitcnt lgkmcnt(0)
	s_setprio 1
	s_barrier
	v_mfma_f32_16x16x32_bf16 v[62:65], v[130:133], v[162:165], 0
	v_mfma_f32_16x16x32_bf16 v[58:61], v[138:141], v[162:165], 0
	v_mfma_f32_16x16x32_bf16 v[42:45], v[138:141], v[170:173], 0
	v_mfma_f32_16x16x32_bf16 v[50:53], v[130:133], v[170:173], 0
	v_mfma_f32_16x16x32_bf16 v[34:37], v[130:133], v[200:203], 0
	v_mfma_f32_16x16x32_bf16 v[26:29], v[138:141], v[200:203], 0
	v_mfma_f32_16x16x32_bf16 v[10:13], v[138:141], v[216:219], 0
	v_mfma_f32_16x16x32_bf16 v[18:21], v[130:133], v[216:219], 0
	v_mfma_f32_16x16x32_bf16 v[62:65], v[134:137], v[166:169], v[62:65]
	v_mfma_f32_16x16x32_bf16 v[58:61], v[142:145], v[166:169], v[58:61]
	v_mfma_f32_16x16x32_bf16 v[42:45], v[142:145], v[174:177], v[42:45]
	v_mfma_f32_16x16x32_bf16 v[50:53], v[134:137], v[174:177], v[50:53]
	v_mfma_f32_16x16x32_bf16 v[34:37], v[134:137], v[212:215], v[34:37]
	v_mfma_f32_16x16x32_bf16 v[26:29], v[142:145], v[212:215], v[26:29]
	v_mfma_f32_16x16x32_bf16 v[10:13], v[142:145], v[224:227], v[10:13]
	v_mfma_f32_16x16x32_bf16 v[18:21], v[134:137], v[224:227], v[18:21]
	v_mfma_f32_16x16x32_bf16 v[54:57], v[146:149], v[162:165], 0
	v_mfma_f32_16x16x32_bf16 v[46:49], v[154:157], v[162:165], 0
	v_mfma_f32_16x16x32_bf16 v[30:33], v[154:157], v[170:173], 0
	v_mfma_f32_16x16x32_bf16 v[38:41], v[146:149], v[170:173], 0
	v_mfma_f32_16x16x32_bf16 v[22:25], v[146:149], v[200:203], 0
	v_mfma_f32_16x16x32_bf16 v[14:17], v[154:157], v[200:203], 0
	v_mfma_f32_16x16x32_bf16 v[2:5], v[154:157], v[216:219], 0
	v_mfma_f32_16x16x32_bf16 v[6:9], v[146:149], v[216:219], 0
	v_mfma_f32_16x16x32_bf16 v[54:57], v[150:153], v[166:169], v[54:57]
	v_mfma_f32_16x16x32_bf16 v[46:49], v[158:161], v[166:169], v[46:49]
	v_mfma_f32_16x16x32_bf16 v[30:33], v[158:161], v[174:177], v[30:33]
	v_mfma_f32_16x16x32_bf16 v[38:41], v[150:153], v[174:177], v[38:41]
	v_mfma_f32_16x16x32_bf16 v[22:25], v[150:153], v[212:215], v[22:25]
	v_mfma_f32_16x16x32_bf16 v[14:17], v[158:161], v[212:215], v[14:17]
	v_mfma_f32_16x16x32_bf16 v[2:5], v[158:161], v[224:227], v[2:5]
	v_mfma_f32_16x16x32_bf16 v[6:9], v[150:153], v[224:227], v[6:9]
	s_barrier
	s_setprio 0
	s_add_i32 s90, 0, 0x18000
	s_add_i32 s91, 0, 0x1c000
	v_add_u32_e32 v142, s90, v189
	v_add_u32_e32 v158, s91, v189
	ds_read_b128 v[130:133], v142
	ds_read_b128 v[134:137], v142 offset:1024
	ds_read_b128 v[138:141], v142 offset:2048
	ds_read_b128 v[142:145], v142 offset:3072
	ds_read_b128 v[146:149], v158
	ds_read_b128 v[150:153], v158 offset:1024
	ds_read_b128 v[154:157], v158 offset:2048
	ds_read_b128 v[158:161], v158 offset:3072
	s_add_u32 s54, s54, 0x100000
	s_addc_u32 s55, s55, 0
	s_mov_b32 m0, s58
	v_lshl_add_u64 v[232:233], s[54:55], 0, v[184:185]
	ds_read_b128 v[162:165], v210 offset:32768
	ds_read_b128 v[166:169], v210 offset:33792
	ds_read_b128 v[170:173], v210 offset:34816
	ds_read_b128 v[174:177], v210 offset:35840
	ds_read_b128 v[200:203], v210 offset:36864
	ds_read_b128 v[212:215], v210 offset:37888
	ds_read_b128 v[216:219], v210 offset:38912
	ds_read_b128 v[224:227], v210 offset:39936
	global_load_lds_dwordx4 v[232:233], off
	v_lshl_add_u64 v[232:233], s[54:55], 0, v[180:181]
	s_mov_b32 m0, s59
	s_nop 0
	global_load_lds_dwordx4 v[232:233], off
	s_waitcnt vmcnt(8)
	s_waitcnt lgkmcnt(0)
	s_setprio 1
	s_barrier
	v_mfma_f32_16x16x32_bf16 v[126:129], v[130:133], v[162:165], v[126:129]
	v_mfma_f32_16x16x32_bf16 v[122:125], v[138:141], v[162:165], v[122:125]
	v_mfma_f32_16x16x32_bf16 v[106:109], v[138:141], v[170:173], v[106:109]
	v_mfma_f32_16x16x32_bf16 v[110:113], v[130:133], v[170:173], v[110:113]
	v_mfma_f32_16x16x32_bf16 v[94:97], v[130:133], v[200:203], v[94:97]
	v_mfma_f32_16x16x32_bf16 v[90:93], v[138:141], v[200:203], v[90:93]
	v_mfma_f32_16x16x32_bf16 v[74:77], v[138:141], v[216:219], v[74:77]
	v_mfma_f32_16x16x32_bf16 v[78:81], v[130:133], v[216:219], v[78:81]
	v_mfma_f32_16x16x32_bf16 v[126:129], v[134:137], v[166:169], v[126:129]
	v_mfma_f32_16x16x32_bf16 v[122:125], v[142:145], v[166:169], v[122:125]
	v_mfma_f32_16x16x32_bf16 v[106:109], v[142:145], v[174:177], v[106:109]
	v_mfma_f32_16x16x32_bf16 v[110:113], v[134:137], v[174:177], v[110:113]
	v_mfma_f32_16x16x32_bf16 v[94:97], v[134:137], v[212:215], v[94:97]
	v_mfma_f32_16x16x32_bf16 v[90:93], v[142:145], v[212:215], v[90:93]
	v_mfma_f32_16x16x32_bf16 v[74:77], v[142:145], v[224:227], v[74:77]
	v_mfma_f32_16x16x32_bf16 v[78:81], v[134:137], v[224:227], v[78:81]
	v_mfma_f32_16x16x32_bf16 v[118:121], v[146:149], v[162:165], v[118:121]
	v_mfma_f32_16x16x32_bf16 v[114:117], v[154:157], v[162:165], v[114:117]
	v_mfma_f32_16x16x32_bf16 v[98:101], v[154:157], v[170:173], v[98:101]
	v_mfma_f32_16x16x32_bf16 v[102:105], v[146:149], v[170:173], v[102:105]
	v_mfma_f32_16x16x32_bf16 v[86:89], v[146:149], v[200:203], v[86:89]
	v_mfma_f32_16x16x32_bf16 v[82:85], v[154:157], v[200:203], v[82:85]
	v_mfma_f32_16x16x32_bf16 v[66:69], v[154:157], v[216:219], v[66:69]
	v_mfma_f32_16x16x32_bf16 v[70:73], v[146:149], v[216:219], v[70:73]
	v_mfma_f32_16x16x32_bf16 v[118:121], v[150:153], v[166:169], v[118:121]
	v_mfma_f32_16x16x32_bf16 v[114:117], v[158:161], v[166:169], v[114:117]
	v_mfma_f32_16x16x32_bf16 v[98:101], v[158:161], v[174:177], v[98:101]
	v_mfma_f32_16x16x32_bf16 v[102:105], v[150:153], v[174:177], v[102:105]
	v_mfma_f32_16x16x32_bf16 v[86:89], v[150:153], v[212:215], v[86:89]
	v_mfma_f32_16x16x32_bf16 v[82:85], v[158:161], v[212:215], v[82:85]
	v_mfma_f32_16x16x32_bf16 v[66:69], v[158:161], v[224:227], v[66:69]
	v_mfma_f32_16x16x32_bf16 v[70:73], v[150:153], v[224:227], v[70:73]
	s_barrier
	s_setprio 0
	s_add_i32 s54, s90, s31
	v_lshl_add_u64 v[204:205], v[204:205], 0, s[8:9]
	s_mov_b32 m0, s54
	ds_read_b128 v[162:165], v210 offset:49152
	ds_read_b128 v[166:169], v210 offset:50176
	ds_read_b128 v[170:173], v210 offset:51200
	ds_read_b128 v[174:177], v210 offset:52224
	ds_read_b128 v[200:203], v210 offset:53248
	ds_read_b128 v[212:215], v210 offset:54272
	ds_read_b128 v[216:219], v210 offset:55296
	ds_read_b128 v[224:227], v210 offset:56320
	global_load_lds_dwordx4 v[204:205], off
	s_add_i32 m0, s54, 0x2000
	s_add_u32 s52, s52, 0x100080
	v_lshl_add_u64 v[204:205], v[220:221], 0, s[8:9]
	s_addc_u32 s53, s53, 0
	s_add_i32 s54, s91, s31
	global_load_lds_dwordx4 v[204:205], off
	v_lshl_add_u64 v[204:205], s[52:53], 0, v[182:183]
	s_mov_b32 m0, s54
	s_nop 0
	global_load_lds_dwordx4 v[204:205], off
	v_lshl_add_u64 v[204:205], s[52:53], 0, v[178:179]
	s_add_i32 m0, s54, 0x2000
	s_nop 0
	global_load_lds_dwordx4 v[204:205], off
	v_lshl_add_u64 v[204:205], v[228:229], 0, s[8:9]
	s_mov_b32 m0, s62
	s_nop 0
	global_load_lds_dwordx4 v[204:205], off
	v_lshl_add_u64 v[204:205], v[230:231], 0, s[8:9]
	s_mov_b32 m0, s63
	s_nop 0
	global_load_lds_dwordx4 v[204:205], off
	s_waitcnt vmcnt(8)
	s_waitcnt lgkmcnt(0)
	s_setprio 1
	s_barrier
	v_mfma_f32_16x16x32_bf16 v[62:65], v[130:133], v[162:165], v[62:65]
	v_mfma_f32_16x16x32_bf16 v[58:61], v[138:141], v[162:165], v[58:61]
	v_mfma_f32_16x16x32_bf16 v[42:45], v[138:141], v[170:173], v[42:45]
	v_mfma_f32_16x16x32_bf16 v[50:53], v[130:133], v[170:173], v[50:53]
	v_mfma_f32_16x16x32_bf16 v[34:37], v[130:133], v[200:203], v[34:37]
	v_mfma_f32_16x16x32_bf16 v[26:29], v[138:141], v[200:203], v[26:29]
	v_mfma_f32_16x16x32_bf16 v[10:13], v[138:141], v[216:219], v[10:13]
	v_mfma_f32_16x16x32_bf16 v[18:21], v[130:133], v[216:219], v[18:21]
	v_mfma_f32_16x16x32_bf16 v[62:65], v[134:137], v[166:169], v[62:65]
	v_mfma_f32_16x16x32_bf16 v[58:61], v[142:145], v[166:169], v[58:61]
	v_mfma_f32_16x16x32_bf16 v[42:45], v[142:145], v[174:177], v[42:45]
	v_mfma_f32_16x16x32_bf16 v[50:53], v[134:137], v[174:177], v[50:53]
	v_mfma_f32_16x16x32_bf16 v[34:37], v[134:137], v[212:215], v[34:37]
	v_mfma_f32_16x16x32_bf16 v[26:29], v[142:145], v[212:215], v[26:29]
	v_mfma_f32_16x16x32_bf16 v[10:13], v[142:145], v[224:227], v[10:13]
	v_mfma_f32_16x16x32_bf16 v[18:21], v[134:137], v[224:227], v[18:21]
	v_mfma_f32_16x16x32_bf16 v[54:57], v[146:149], v[162:165], v[54:57]
	v_mfma_f32_16x16x32_bf16 v[46:49], v[154:157], v[162:165], v[46:49]
	v_mfma_f32_16x16x32_bf16 v[30:33], v[154:157], v[170:173], v[30:33]
	v_mfma_f32_16x16x32_bf16 v[38:41], v[146:149], v[170:173], v[38:41]
	v_mfma_f32_16x16x32_bf16 v[22:25], v[146:149], v[200:203], v[22:25]
	v_mfma_f32_16x16x32_bf16 v[14:17], v[154:157], v[200:203], v[14:17]
	v_mfma_f32_16x16x32_bf16 v[2:5], v[154:157], v[216:219], v[2:5]
	v_mfma_f32_16x16x32_bf16 v[6:9], v[146:149], v[216:219], v[6:9]
	v_mfma_f32_16x16x32_bf16 v[54:57], v[150:153], v[166:169], v[54:57]
	v_mfma_f32_16x16x32_bf16 v[46:49], v[158:161], v[166:169], v[46:49]
	v_mfma_f32_16x16x32_bf16 v[30:33], v[158:161], v[174:177], v[30:33]
	v_mfma_f32_16x16x32_bf16 v[38:41], v[150:153], v[174:177], v[38:41]
	v_mfma_f32_16x16x32_bf16 v[22:25], v[150:153], v[212:215], v[22:25]
	v_mfma_f32_16x16x32_bf16 v[14:17], v[158:161], v[212:215], v[14:17]
	v_mfma_f32_16x16x32_bf16 v[2:5], v[158:161], v[224:227], v[2:5]
	v_mfma_f32_16x16x32_bf16 v[6:9], v[150:153], v[224:227], v[6:9]
	s_barrier
	s_setprio 0
	s_add_i32 s89, s89, 2
	s_add_u32 s50, s50, 0x100
	s_addc_u32 s51, s51, 0
	s_add_u32 s87, s87, 0x100
	s_addc_u32 s88, s88, 0
.LBB0_224:
	ds_read_b128 v[130:133], v208
	ds_read_b128 v[134:137], v208 offset:1024
	ds_read_b128 v[138:141], v208 offset:2048
	ds_read_b128 v[142:145], v208 offset:3072
	ds_read_b128 v[146:149], v209
	ds_read_b128 v[150:153], v209 offset:1024
	ds_read_b128 v[154:157], v209 offset:2048
	ds_read_b128 v[158:161], v209 offset:3072
	s_add_u32 s52, s50, 0xfff00080
	s_addc_u32 s53, s51, -1
	s_cmp_eq_u32 s89, 60
	s_cselect_b32 s55, s43, s53
	s_cselect_b32 s54, s85, s52
	s_cselect_b32 s53, s41, s88
	s_cselect_b32 s52, s86, s87
	v_lshl_add_u64 v[204:205], s[50:51], 0, v[192:193]
	s_add_i32 m0, s56, 0xc000
	ds_read_b128 v[162:165], v210
	ds_read_b128 v[166:169], v210 offset:1024
	ds_read_b128 v[170:173], v210 offset:2048
	ds_read_b128 v[174:177], v210 offset:3072
	ds_read_b128 v[200:203], v210 offset:4096
	ds_read_b128 v[212:215], v210 offset:5120
	ds_read_b128 v[216:219], v210 offset:6144
	ds_read_b128 v[224:227], v210 offset:7168
	global_load_lds_dwordx4 v[204:205], off
	v_lshl_add_u64 v[204:205], s[50:51], 0, v[194:195]
	s_add_i32 m0, s56, 0xe000
	s_nop 0
	global_load_lds_dwordx4 v[204:205], off
	s_waitcnt vmcnt(8)
	s_waitcnt lgkmcnt(0)
	s_setprio 1
	s_barrier
	v_mfma_f32_16x16x32_bf16 v[126:129], v[130:133], v[162:165], v[126:129]
	v_mfma_f32_16x16x32_bf16 v[122:125], v[138:141], v[162:165], v[122:125]
	v_mfma_f32_16x16x32_bf16 v[106:109], v[138:141], v[170:173], v[106:109]
	v_mfma_f32_16x16x32_bf16 v[110:113], v[130:133], v[170:173], v[110:113]
	v_mfma_f32_16x16x32_bf16 v[94:97], v[130:133], v[200:203], v[94:97]
	v_mfma_f32_16x16x32_bf16 v[90:93], v[138:141], v[200:203], v[90:93]
	v_mfma_f32_16x16x32_bf16 v[74:77], v[138:141], v[216:219], v[74:77]
	v_mfma_f32_16x16x32_bf16 v[78:81], v[130:133], v[216:219], v[78:81]
	v_mfma_f32_16x16x32_bf16 v[126:129], v[134:137], v[166:169], v[126:129]
	v_mfma_f32_16x16x32_bf16 v[122:125], v[142:145], v[166:169], v[122:125]
	v_mfma_f32_16x16x32_bf16 v[106:109], v[142:145], v[174:177], v[106:109]
	v_mfma_f32_16x16x32_bf16 v[110:113], v[134:137], v[174:177], v[110:113]
	v_mfma_f32_16x16x32_bf16 v[94:97], v[134:137], v[212:215], v[94:97]
	v_mfma_f32_16x16x32_bf16 v[90:93], v[142:145], v[212:215], v[90:93]
	v_mfma_f32_16x16x32_bf16 v[74:77], v[142:145], v[224:227], v[74:77]
	v_mfma_f32_16x16x32_bf16 v[78:81], v[134:137], v[224:227], v[78:81]
	v_mfma_f32_16x16x32_bf16 v[118:121], v[146:149], v[162:165], v[118:121]
	v_mfma_f32_16x16x32_bf16 v[114:117], v[154:157], v[162:165], v[114:117]
	v_mfma_f32_16x16x32_bf16 v[98:101], v[154:157], v[170:173], v[98:101]
	v_mfma_f32_16x16x32_bf16 v[102:105], v[146:149], v[170:173], v[102:105]
	v_mfma_f32_16x16x32_bf16 v[86:89], v[146:149], v[200:203], v[86:89]
	v_mfma_f32_16x16x32_bf16 v[82:85], v[154:157], v[200:203], v[82:85]
	v_mfma_f32_16x16x32_bf16 v[66:69], v[154:157], v[216:219], v[66:69]
	v_mfma_f32_16x16x32_bf16 v[70:73], v[146:149], v[216:219], v[70:73]
	v_mfma_f32_16x16x32_bf16 v[118:121], v[150:153], v[166:169], v[118:121]
	v_mfma_f32_16x16x32_bf16 v[114:117], v[158:161], v[166:169], v[114:117]
	v_mfma_f32_16x16x32_bf16 v[98:101], v[158:161], v[174:177], v[98:101]
	v_mfma_f32_16x16x32_bf16 v[102:105], v[150:153], v[174:177], v[102:105]
	v_mfma_f32_16x16x32_bf16 v[86:89], v[150:153], v[212:215], v[86:89]
	v_mfma_f32_16x16x32_bf16 v[82:85], v[158:161], v[212:215], v[82:85]
	v_mfma_f32_16x16x32_bf16 v[66:69], v[158:161], v[224:227], v[66:69]
	v_mfma_f32_16x16x32_bf16 v[70:73], v[150:153], v[224:227], v[70:73]
	s_barrier
	s_setprio 0
	s_add_i32 s90, s65, s31
	v_lshl_add_u64 v[204:205], s[52:53], 0, v[182:183]
	s_mov_b32 m0, s90
	ds_read_b128 v[162:165], v210 offset:16384
	ds_read_b128 v[166:169], v210 offset:17408
	ds_read_b128 v[170:173], v210 offset:18432
	ds_read_b128 v[174:177], v210 offset:19456
	ds_read_b128 v[200:203], v210 offset:20480
	ds_read_b128 v[212:215], v210 offset:21504
	ds_read_b128 v[216:219], v210 offset:22528
	ds_read_b128 v[224:227], v210 offset:23552
	global_load_lds_dwordx4 v[204:205], off
	s_add_i32 m0, s90, 0x2000
	s_add_u32 s90, s52, 0x100000
	v_lshl_add_u64 v[220:221], s[52:53], 0, v[178:179]
	s_addc_u32 s91, s53, 0
	s_add_i32 s92, s66, s31
	global_load_lds_dwordx4 v[220:221], off
	v_lshl_add_u64 v[228:229], s[90:91], 0, v[182:183]
	s_mov_b32 m0, s92
	v_lshl_add_u64 v[230:231], s[54:55], 0, v[180:181]
	global_load_lds_dwordx4 v[228:229], off
	v_lshl_add_u64 v[228:229], s[90:91], 0, v[178:179]
	s_add_i32 m0, s92, 0x2000
	s_nop 0
	global_load_lds_dwordx4 v[228:229], off
	v_lshl_add_u64 v[228:229], s[54:55], 0, v[184:185]
	s_mov_b32 m0, s56
	s_nop 0
	global_load_lds_dwordx4 v[228:229], off
	s_mov_b32 m0, s57
	s_nop 0
	global_load_lds_dwordx4 v[230:231], off
	s_waitcnt vmcnt(8)
	s_waitcnt lgkmcnt(0)
	s_setprio 1
	s_barrier
	v_mfma_f32_16x16x32_bf16 v[62:65], v[130:133], v[162:165], v[62:65]
	v_mfma_f32_16x16x32_bf16 v[58:61], v[138:141], v[162:165], v[58:61]
	v_mfma_f32_16x16x32_bf16 v[42:45], v[138:141], v[170:173], v[42:45]
	v_mfma_f32_16x16x32_bf16 v[50:53], v[130:133], v[170:173], v[50:53]
	v_mfma_f32_16x16x32_bf16 v[34:37], v[130:133], v[200:203], v[34:37]
	v_mfma_f32_16x16x32_bf16 v[26:29], v[138:141], v[200:203], v[26:29]
	v_mfma_f32_16x16x32_bf16 v[10:13], v[138:141], v[216:219], v[10:13]
	v_mfma_f32_16x16x32_bf16 v[18:21], v[130:133], v[216:219], v[18:21]
	v_mfma_f32_16x16x32_bf16 v[62:65], v[134:137], v[166:169], v[62:65]
	v_mfma_f32_16x16x32_bf16 v[58:61], v[142:145], v[166:169], v[58:61]
	v_mfma_f32_16x16x32_bf16 v[42:45], v[142:145], v[174:177], v[42:45]
	v_mfma_f32_16x16x32_bf16 v[50:53], v[134:137], v[174:177], v[50:53]
	v_mfma_f32_16x16x32_bf16 v[34:37], v[134:137], v[212:215], v[34:37]
	v_mfma_f32_16x16x32_bf16 v[26:29], v[142:145], v[212:215], v[26:29]
	v_mfma_f32_16x16x32_bf16 v[10:13], v[142:145], v[224:227], v[10:13]
	v_mfma_f32_16x16x32_bf16 v[18:21], v[134:137], v[224:227], v[18:21]
	v_mfma_f32_16x16x32_bf16 v[54:57], v[146:149], v[162:165], v[54:57]
	v_mfma_f32_16x16x32_bf16 v[46:49], v[154:157], v[162:165], v[46:49]
	v_mfma_f32_16x16x32_bf16 v[30:33], v[154:157], v[170:173], v[30:33]
	v_mfma_f32_16x16x32_bf16 v[38:41], v[146:149], v[170:173], v[38:41]
	v_mfma_f32_16x16x32_bf16 v[22:25], v[146:149], v[200:203], v[22:25]
	v_mfma_f32_16x16x32_bf16 v[14:17], v[154:157], v[200:203], v[14:17]
	v_mfma_f32_16x16x32_bf16 v[2:5], v[154:157], v[216:219], v[2:5]
	v_mfma_f32_16x16x32_bf16 v[6:9], v[146:149], v[216:219], v[6:9]
	v_mfma_f32_16x16x32_bf16 v[54:57], v[150:153], v[166:169], v[54:57]
	v_mfma_f32_16x16x32_bf16 v[46:49], v[158:161], v[166:169], v[46:49]
	v_mfma_f32_16x16x32_bf16 v[30:33], v[158:161], v[174:177], v[30:33]
	v_mfma_f32_16x16x32_bf16 v[38:41], v[150:153], v[174:177], v[38:41]
	v_mfma_f32_16x16x32_bf16 v[22:25], v[150:153], v[212:215], v[22:25]
	v_mfma_f32_16x16x32_bf16 v[14:17], v[158:161], v[212:215], v[14:17]
	v_mfma_f32_16x16x32_bf16 v[2:5], v[158:161], v[224:227], v[2:5]
	v_mfma_f32_16x16x32_bf16 v[6:9], v[150:153], v[224:227], v[6:9]
	s_barrier
	s_setprio 0
	s_add_i32 s90, 0, 0x18000
	s_add_i32 s91, 0, 0x1c000
	v_add_u32_e32 v142, s90, v189
	v_add_u32_e32 v158, s91, v189
	ds_read_b128 v[130:133], v142
	ds_read_b128 v[134:137], v142 offset:1024
	ds_read_b128 v[138:141], v142 offset:2048
	ds_read_b128 v[142:145], v142 offset:3072
	ds_read_b128 v[146:149], v158
	ds_read_b128 v[150:153], v158 offset:1024
	ds_read_b128 v[154:157], v158 offset:2048
	ds_read_b128 v[158:161], v158 offset:3072
	s_add_u32 s54, s54, 0x100000
	s_addc_u32 s55, s55, 0
	s_mov_b32 m0, s58
	v_lshl_add_u64 v[232:233], s[54:55], 0, v[184:185]
	ds_read_b128 v[162:165], v210 offset:32768
	ds_read_b128 v[166:169], v210 offset:33792
	ds_read_b128 v[170:173], v210 offset:34816
	ds_read_b128 v[174:177], v210 offset:35840
	ds_read_b128 v[200:203], v210 offset:36864
	ds_read_b128 v[212:215], v210 offset:37888
	ds_read_b128 v[216:219], v210 offset:38912
	ds_read_b128 v[224:227], v210 offset:39936
	global_load_lds_dwordx4 v[232:233], off
	v_lshl_add_u64 v[232:233], s[54:55], 0, v[180:181]
	s_mov_b32 m0, s59
	s_nop 0
	global_load_lds_dwordx4 v[232:233], off
	s_waitcnt vmcnt(8)
	s_waitcnt lgkmcnt(0)
	s_setprio 1
	s_barrier
	v_mfma_f32_16x16x32_bf16 v[126:129], v[130:133], v[162:165], v[126:129]
	v_mfma_f32_16x16x32_bf16 v[122:125], v[138:141], v[162:165], v[122:125]
	v_mfma_f32_16x16x32_bf16 v[106:109], v[138:141], v[170:173], v[106:109]
	v_mfma_f32_16x16x32_bf16 v[110:113], v[130:133], v[170:173], v[110:113]
	v_mfma_f32_16x16x32_bf16 v[94:97], v[130:133], v[200:203], v[94:97]
	v_mfma_f32_16x16x32_bf16 v[90:93], v[138:141], v[200:203], v[90:93]
	v_mfma_f32_16x16x32_bf16 v[74:77], v[138:141], v[216:219], v[74:77]
	v_mfma_f32_16x16x32_bf16 v[78:81], v[130:133], v[216:219], v[78:81]
	v_mfma_f32_16x16x32_bf16 v[126:129], v[134:137], v[166:169], v[126:129]
	v_mfma_f32_16x16x32_bf16 v[122:125], v[142:145], v[166:169], v[122:125]
	v_mfma_f32_16x16x32_bf16 v[106:109], v[142:145], v[174:177], v[106:109]
	v_mfma_f32_16x16x32_bf16 v[110:113], v[134:137], v[174:177], v[110:113]
	v_mfma_f32_16x16x32_bf16 v[94:97], v[134:137], v[212:215], v[94:97]
	v_mfma_f32_16x16x32_bf16 v[90:93], v[142:145], v[212:215], v[90:93]
	v_mfma_f32_16x16x32_bf16 v[74:77], v[142:145], v[224:227], v[74:77]
	v_mfma_f32_16x16x32_bf16 v[78:81], v[134:137], v[224:227], v[78:81]
	v_mfma_f32_16x16x32_bf16 v[118:121], v[146:149], v[162:165], v[118:121]
	v_mfma_f32_16x16x32_bf16 v[114:117], v[154:157], v[162:165], v[114:117]
	v_mfma_f32_16x16x32_bf16 v[98:101], v[154:157], v[170:173], v[98:101]
	v_mfma_f32_16x16x32_bf16 v[102:105], v[146:149], v[170:173], v[102:105]
	v_mfma_f32_16x16x32_bf16 v[86:89], v[146:149], v[200:203], v[86:89]
	v_mfma_f32_16x16x32_bf16 v[82:85], v[154:157], v[200:203], v[82:85]
	v_mfma_f32_16x16x32_bf16 v[66:69], v[154:157], v[216:219], v[66:69]
	v_mfma_f32_16x16x32_bf16 v[70:73], v[146:149], v[216:219], v[70:73]
	v_mfma_f32_16x16x32_bf16 v[118:121], v[150:153], v[166:169], v[118:121]
	v_mfma_f32_16x16x32_bf16 v[114:117], v[158:161], v[166:169], v[114:117]
	v_mfma_f32_16x16x32_bf16 v[98:101], v[158:161], v[174:177], v[98:101]
	v_mfma_f32_16x16x32_bf16 v[102:105], v[150:153], v[174:177], v[102:105]
	v_mfma_f32_16x16x32_bf16 v[86:89], v[150:153], v[212:215], v[86:89]
	v_mfma_f32_16x16x32_bf16 v[82:85], v[158:161], v[212:215], v[82:85]
	v_mfma_f32_16x16x32_bf16 v[66:69], v[158:161], v[224:227], v[66:69]
	v_mfma_f32_16x16x32_bf16 v[70:73], v[150:153], v[224:227], v[70:73]
	s_barrier
	s_setprio 0
	s_add_i32 s54, s90, s31
	v_lshl_add_u64 v[204:205], v[204:205], 0, s[8:9]
	s_mov_b32 m0, s54
	ds_read_b128 v[162:165], v210 offset:49152
	ds_read_b128 v[166:169], v210 offset:50176
	ds_read_b128 v[170:173], v210 offset:51200
	ds_read_b128 v[174:177], v210 offset:52224
	ds_read_b128 v[200:203], v210 offset:53248
	ds_read_b128 v[212:215], v210 offset:54272
	ds_read_b128 v[216:219], v210 offset:55296
	ds_read_b128 v[224:227], v210 offset:56320
	global_load_lds_dwordx4 v[204:205], off
	s_add_i32 m0, s54, 0x2000
	s_add_u32 s52, s52, 0x100080
	v_lshl_add_u64 v[204:205], v[220:221], 0, s[8:9]
	s_addc_u32 s53, s53, 0
	s_add_i32 s54, s91, s31
	global_load_lds_dwordx4 v[204:205], off
	v_lshl_add_u64 v[204:205], s[52:53], 0, v[182:183]
	s_mov_b32 m0, s54
	s_nop 0
	global_load_lds_dwordx4 v[204:205], off
	v_lshl_add_u64 v[204:205], s[52:53], 0, v[178:179]
	s_add_i32 m0, s54, 0x2000
	s_nop 0
	global_load_lds_dwordx4 v[204:205], off
	v_lshl_add_u64 v[204:205], v[228:229], 0, s[8:9]
	s_mov_b32 m0, s62
	s_nop 0
	global_load_lds_dwordx4 v[204:205], off
	v_lshl_add_u64 v[204:205], v[230:231], 0, s[8:9]
	s_mov_b32 m0, s63
	s_nop 0
	global_load_lds_dwordx4 v[204:205], off
	s_waitcnt vmcnt(8)
	s_waitcnt lgkmcnt(0)
	s_setprio 1
	s_barrier
	v_mfma_f32_16x16x32_bf16 v[62:65], v[130:133], v[162:165], v[62:65]
	v_mfma_f32_16x16x32_bf16 v[58:61], v[138:141], v[162:165], v[58:61]
	v_mfma_f32_16x16x32_bf16 v[42:45], v[138:141], v[170:173], v[42:45]
	v_mfma_f32_16x16x32_bf16 v[50:53], v[130:133], v[170:173], v[50:53]
	v_mfma_f32_16x16x32_bf16 v[34:37], v[130:133], v[200:203], v[34:37]
	v_mfma_f32_16x16x32_bf16 v[26:29], v[138:141], v[200:203], v[26:29]
	v_mfma_f32_16x16x32_bf16 v[10:13], v[138:141], v[216:219], v[10:13]
	v_mfma_f32_16x16x32_bf16 v[18:21], v[130:133], v[216:219], v[18:21]
	v_mfma_f32_16x16x32_bf16 v[62:65], v[134:137], v[166:169], v[62:65]
	v_mfma_f32_16x16x32_bf16 v[58:61], v[142:145], v[166:169], v[58:61]
	v_mfma_f32_16x16x32_bf16 v[42:45], v[142:145], v[174:177], v[42:45]
	v_mfma_f32_16x16x32_bf16 v[50:53], v[134:137], v[174:177], v[50:53]
	v_mfma_f32_16x16x32_bf16 v[34:37], v[134:137], v[212:215], v[34:37]
	v_mfma_f32_16x16x32_bf16 v[26:29], v[142:145], v[212:215], v[26:29]
	v_mfma_f32_16x16x32_bf16 v[10:13], v[142:145], v[224:227], v[10:13]
	v_mfma_f32_16x16x32_bf16 v[18:21], v[134:137], v[224:227], v[18:21]
	v_mfma_f32_16x16x32_bf16 v[54:57], v[146:149], v[162:165], v[54:57]
	v_mfma_f32_16x16x32_bf16 v[46:49], v[154:157], v[162:165], v[46:49]
	v_mfma_f32_16x16x32_bf16 v[30:33], v[154:157], v[170:173], v[30:33]
	v_mfma_f32_16x16x32_bf16 v[38:41], v[146:149], v[170:173], v[38:41]
	v_mfma_f32_16x16x32_bf16 v[22:25], v[146:149], v[200:203], v[22:25]
	v_mfma_f32_16x16x32_bf16 v[14:17], v[154:157], v[200:203], v[14:17]
	v_mfma_f32_16x16x32_bf16 v[2:5], v[154:157], v[216:219], v[2:5]
	v_mfma_f32_16x16x32_bf16 v[6:9], v[146:149], v[216:219], v[6:9]
	v_mfma_f32_16x16x32_bf16 v[54:57], v[150:153], v[166:169], v[54:57]
	v_mfma_f32_16x16x32_bf16 v[46:49], v[158:161], v[166:169], v[46:49]
	v_mfma_f32_16x16x32_bf16 v[30:33], v[158:161], v[174:177], v[30:33]
	v_mfma_f32_16x16x32_bf16 v[38:41], v[150:153], v[174:177], v[38:41]
	v_mfma_f32_16x16x32_bf16 v[22:25], v[150:153], v[212:215], v[22:25]
	v_mfma_f32_16x16x32_bf16 v[14:17], v[158:161], v[212:215], v[14:17]
	v_mfma_f32_16x16x32_bf16 v[2:5], v[158:161], v[224:227], v[2:5]
	v_mfma_f32_16x16x32_bf16 v[6:9], v[150:153], v[224:227], v[6:9]
	s_barrier
	s_setprio 0
	s_add_i32 s89, s89, 2
	s_add_u32 s50, s50, 0x100
	s_addc_u32 s51, s51, 0
	s_add_u32 s87, s87, 0x100
	s_addc_u32 s88, s88, 0
	s_cmp_gt_u32 s89, 61
	s_cbranch_scc0 .LBB0_224
	s_and_b64 vcc, exec, s[10:11]
	s_cbranch_vccz .LBB0_229
	s_barrier
	v_lshl_add_u32 v200, s0, 8, v1
	s_cmp_gt_i32 s84, 15
	s_mov_b64 s[50:51], -1
	s_cbranch_scc1 .LBB0_230

.Lpeelb:
	v_add_u32_e32 v142, s51, v220
	v_add_u32_e32 v158, s81, v220
	ds_read_b128 v[130:133], v142
	ds_read_b128 v[134:137], v142 offset:1024
	ds_read_b128 v[138:141], v142 offset:2048
	ds_read_b128 v[142:145], v142 offset:3072
	ds_read_b128 v[146:149], v158
	ds_read_b128 v[150:153], v158 offset:1024
	ds_read_b128 v[154:157], v158 offset:2048
	ds_read_b128 v[158:161], v158 offset:3072
	s_add_u32 s16, s0, 0xfff00080
	s_addc_u32 s17, s1, -1
	s_cmp_eq_u32 s26, 60
	s_cselect_b32 s19, s20, s17
	s_cselect_b32 s18, s21, s16
	s_cselect_b32 s17, s22, s25
	s_cselect_b32 s16, s23, s24
	v_lshl_add_u64 v[218:219], s[0:1], 0, v[194:195]
	s_add_i32 m0, s31, 0xc000
	ds_read_b128 v[162:165], v233
	ds_read_b128 v[166:169], v233 offset:1024
	ds_read_b128 v[170:173], v233 offset:2048
	ds_read_b128 v[174:177], v233 offset:3072
	ds_read_b128 v[202:205], v233 offset:4096
	ds_read_b128 v[206:209], v233 offset:5120
	ds_read_b128 v[210:213], v233 offset:6144
	ds_read_b128 v[214:217], v233 offset:7168
	global_load_lds_dwordx4 v[218:219], off
	v_lshl_add_u64 v[218:219], s[0:1], 0, v[196:197]
	s_add_i32 m0, s31, 0xe000
	s_nop 0
	global_load_lds_dwordx4 v[218:219], off
	s_waitcnt vmcnt(8)
	s_waitcnt lgkmcnt(0)
	s_setprio 1
	s_barrier
	v_mfma_f32_16x16x32_bf16 v[90:93], v[130:133], v[162:165], 0
	v_mfma_f32_16x16x32_bf16 v[58:61], v[138:141], v[162:165], 0
	v_mfma_f32_16x16x32_bf16 v[66:69], v[138:141], v[170:173], 0
	v_mfma_f32_16x16x32_bf16 v[98:101], v[130:133], v[170:173], 0
	v_mfma_f32_16x16x32_bf16 v[102:105], v[130:133], v[202:205], 0
	v_mfma_f32_16x16x32_bf16 v[70:73], v[138:141], v[202:205], 0
	v_mfma_f32_16x16x32_bf16 v[78:81], v[138:141], v[210:213], 0
	v_mfma_f32_16x16x32_bf16 v[110:113], v[130:133], v[210:213], 0
	v_mfma_f32_16x16x32_bf16 v[90:93], v[134:137], v[166:169], v[90:93]
	v_mfma_f32_16x16x32_bf16 v[58:61], v[142:145], v[166:169], v[58:61]
	v_mfma_f32_16x16x32_bf16 v[66:69], v[142:145], v[174:177], v[66:69]
	v_mfma_f32_16x16x32_bf16 v[98:101], v[134:137], v[174:177], v[98:101]
	v_mfma_f32_16x16x32_bf16 v[102:105], v[134:137], v[206:209], v[102:105]
	v_mfma_f32_16x16x32_bf16 v[70:73], v[142:145], v[206:209], v[70:73]
	v_mfma_f32_16x16x32_bf16 v[78:81], v[142:145], v[214:217], v[78:81]
	v_mfma_f32_16x16x32_bf16 v[110:113], v[134:137], v[214:217], v[110:113]
	v_mfma_f32_16x16x32_bf16 v[26:29], v[146:149], v[162:165], 0
	v_mfma_f32_16x16x32_bf16 v[2:5], v[154:157], v[162:165], 0
	v_mfma_f32_16x16x32_bf16 v[6:9], v[154:157], v[170:173], 0
	v_mfma_f32_16x16x32_bf16 v[34:37], v[146:149], v[170:173], 0
	v_mfma_f32_16x16x32_bf16 v[38:41], v[146:149], v[202:205], 0
	v_mfma_f32_16x16x32_bf16 v[10:13], v[154:157], v[202:205], 0
	v_mfma_f32_16x16x32_bf16 v[14:17], v[154:157], v[210:213], 0
	v_mfma_f32_16x16x32_bf16 v[46:49], v[146:149], v[210:213], 0
	v_mfma_f32_16x16x32_bf16 v[26:29], v[150:153], v[166:169], v[26:29]
	v_mfma_f32_16x16x32_bf16 v[2:5], v[158:161], v[166:169], v[2:5]
	v_mfma_f32_16x16x32_bf16 v[6:9], v[158:161], v[174:177], v[6:9]
	v_mfma_f32_16x16x32_bf16 v[34:37], v[150:153], v[174:177], v[34:37]
	v_mfma_f32_16x16x32_bf16 v[38:41], v[150:153], v[206:209], v[38:41]
	v_mfma_f32_16x16x32_bf16 v[10:13], v[158:161], v[206:209], v[10:13]
	v_mfma_f32_16x16x32_bf16 v[14:17], v[158:161], v[214:217], v[14:17]
	v_mfma_f32_16x16x32_bf16 v[46:49], v[150:153], v[214:217], v[46:49]
	s_barrier
	s_setprio 0
	s_add_i32 s27, s51, s15
	v_lshl_add_u64 v[218:219], s[16:17], 0, v[178:179]
	s_mov_b32 m0, s27
	ds_read_b128 v[162:165], v233 offset:16384
	ds_read_b128 v[166:169], v233 offset:17408
	ds_read_b128 v[170:173], v233 offset:18432
	ds_read_b128 v[174:177], v233 offset:19456
	ds_read_b128 v[202:205], v233 offset:20480
	ds_read_b128 v[206:209], v233 offset:21504
	ds_read_b128 v[210:213], v233 offset:22528
	ds_read_b128 v[214:217], v233 offset:23552
	global_load_lds_dwordx4 v[218:219], off
	s_add_i32 m0, s27, 0x2000
	s_add_u32 s62, s16, 0x100000
	v_lshl_add_u64 v[242:243], s[16:17], 0, v[180:181]
	s_addc_u32 s63, s17, 0
	s_add_i32 s27, s81, s15
	global_load_lds_dwordx4 v[242:243], off
	v_lshl_add_u64 v[244:245], s[62:63], 0, v[178:179]
	s_mov_b32 m0, s27
	v_lshl_add_u64 v[246:247], s[18:19], 0, v[180:181]
	global_load_lds_dwordx4 v[244:245], off
	v_lshl_add_u64 v[244:245], s[62:63], 0, v[180:181]
	s_add_i32 m0, s27, 0x2000
	s_nop 0
	global_load_lds_dwordx4 v[244:245], off
	v_lshl_add_u64 v[244:245], s[18:19], 0, v[178:179]
	s_mov_b32 m0, s31
	s_nop 0
	global_load_lds_dwordx4 v[244:245], off
	s_mov_b32 m0, s34
	s_nop 0
	global_load_lds_dwordx4 v[246:247], off
	s_waitcnt vmcnt(8)
	s_waitcnt lgkmcnt(0)
	s_setprio 1
	s_barrier
	v_mfma_f32_16x16x32_bf16 v[114:117], v[130:133], v[162:165], 0
	v_mfma_f32_16x16x32_bf16 v[82:85], v[138:141], v[162:165], 0
	v_mfma_f32_16x16x32_bf16 v[86:89], v[138:141], v[170:173], 0
	v_mfma_f32_16x16x32_bf16 v[118:121], v[130:133], v[170:173], 0
	v_mfma_f32_16x16x32_bf16 v[122:125], v[130:133], v[202:205], 0
	v_mfma_f32_16x16x32_bf16 v[94:97], v[138:141], v[202:205], 0
	v_mfma_f32_16x16x32_bf16 v[106:109], v[138:141], v[210:213], 0
	v_mfma_f32_16x16x32_bf16 v[126:129], v[130:133], v[210:213], 0
	v_mfma_f32_16x16x32_bf16 v[114:117], v[134:137], v[166:169], v[114:117]
	v_mfma_f32_16x16x32_bf16 v[82:85], v[142:145], v[166:169], v[82:85]
	v_mfma_f32_16x16x32_bf16 v[86:89], v[142:145], v[174:177], v[86:89]
	v_mfma_f32_16x16x32_bf16 v[118:121], v[134:137], v[174:177], v[118:121]
	v_mfma_f32_16x16x32_bf16 v[122:125], v[134:137], v[206:209], v[122:125]
	v_mfma_f32_16x16x32_bf16 v[94:97], v[142:145], v[206:209], v[94:97]
	v_mfma_f32_16x16x32_bf16 v[106:109], v[142:145], v[214:217], v[106:109]
	v_mfma_f32_16x16x32_bf16 v[126:129], v[134:137], v[214:217], v[126:129]
	v_mfma_f32_16x16x32_bf16 v[50:53], v[146:149], v[162:165], 0
	v_mfma_f32_16x16x32_bf16 v[18:21], v[154:157], v[162:165], 0
	v_mfma_f32_16x16x32_bf16 v[22:25], v[154:157], v[170:173], 0
	v_mfma_f32_16x16x32_bf16 v[54:57], v[146:149], v[170:173], 0
	v_mfma_f32_16x16x32_bf16 v[62:65], v[146:149], v[202:205], 0
	v_mfma_f32_16x16x32_bf16 v[30:33], v[154:157], v[202:205], 0
	v_mfma_f32_16x16x32_bf16 v[42:45], v[154:157], v[210:213], 0
	v_mfma_f32_16x16x32_bf16 v[74:77], v[146:149], v[210:213], 0
	v_mfma_f32_16x16x32_bf16 v[50:53], v[150:153], v[166:169], v[50:53]
	v_mfma_f32_16x16x32_bf16 v[18:21], v[158:161], v[166:169], v[18:21]
	v_mfma_f32_16x16x32_bf16 v[22:25], v[158:161], v[174:177], v[22:25]
	v_mfma_f32_16x16x32_bf16 v[54:57], v[150:153], v[174:177], v[54:57]
	v_mfma_f32_16x16x32_bf16 v[62:65], v[150:153], v[206:209], v[62:65]
	v_mfma_f32_16x16x32_bf16 v[30:33], v[158:161], v[206:209], v[30:33]
	v_mfma_f32_16x16x32_bf16 v[42:45], v[158:161], v[214:217], v[42:45]
	v_mfma_f32_16x16x32_bf16 v[74:77], v[150:153], v[214:217], v[74:77]
	s_barrier
	s_setprio 0
	s_add_i32 s27, 0, 0x18000
	s_add_i32 s59, 0, 0x1c000
	v_add_u32_e32 v142, s27, v220
	v_add_u32_e32 v158, s59, v220
	ds_read_b128 v[130:133], v142
	ds_read_b128 v[134:137], v142 offset:1024
	ds_read_b128 v[138:141], v142 offset:2048
	ds_read_b128 v[142:145], v142 offset:3072
	ds_read_b128 v[146:149], v158
	ds_read_b128 v[150:153], v158 offset:1024
	ds_read_b128 v[154:157], v158 offset:2048
	ds_read_b128 v[158:161], v158 offset:3072
	s_add_u32 s18, s18, 0x100000
	s_addc_u32 s19, s19, 0
	s_mov_b32 m0, s35
	v_lshl_add_u64 v[248:249], s[18:19], 0, v[178:179]
	ds_read_b128 v[162:165], v233 offset:32768
	ds_read_b128 v[166:169], v233 offset:33792
	ds_read_b128 v[170:173], v233 offset:34816
	ds_read_b128 v[174:177], v233 offset:35840
	ds_read_b128 v[202:205], v233 offset:36864
	ds_read_b128 v[206:209], v233 offset:37888
	ds_read_b128 v[210:213], v233 offset:38912
	ds_read_b128 v[214:217], v233 offset:39936
	global_load_lds_dwordx4 v[248:249], off
	v_lshl_add_u64 v[248:249], s[18:19], 0, v[180:181]
	s_mov_b32 m0, s86
	s_nop 0
	global_load_lds_dwordx4 v[248:249], off
	s_waitcnt vmcnt(8)
	s_waitcnt lgkmcnt(0)
	s_setprio 1
	s_barrier
	v_mfma_f32_16x16x32_bf16 v[90:93], v[130:133], v[162:165], v[90:93]
	v_mfma_f32_16x16x32_bf16 v[58:61], v[138:141], v[162:165], v[58:61]
	v_mfma_f32_16x16x32_bf16 v[66:69], v[138:141], v[170:173], v[66:69]
	v_mfma_f32_16x16x32_bf16 v[98:101], v[130:133], v[170:173], v[98:101]
	v_mfma_f32_16x16x32_bf16 v[102:105], v[130:133], v[202:205], v[102:105]
	v_mfma_f32_16x16x32_bf16 v[70:73], v[138:141], v[202:205], v[70:73]
	v_mfma_f32_16x16x32_bf16 v[78:81], v[138:141], v[210:213], v[78:81]
	v_mfma_f32_16x16x32_bf16 v[110:113], v[130:133], v[210:213], v[110:113]
	v_mfma_f32_16x16x32_bf16 v[90:93], v[134:137], v[166:169], v[90:93]
	v_mfma_f32_16x16x32_bf16 v[58:61], v[142:145], v[166:169], v[58:61]
	v_mfma_f32_16x16x32_bf16 v[66:69], v[142:145], v[174:177], v[66:69]
	v_mfma_f32_16x16x32_bf16 v[98:101], v[134:137], v[174:177], v[98:101]
	v_mfma_f32_16x16x32_bf16 v[102:105], v[134:137], v[206:209], v[102:105]
	v_mfma_f32_16x16x32_bf16 v[70:73], v[142:145], v[206:209], v[70:73]
	v_mfma_f32_16x16x32_bf16 v[78:81], v[142:145], v[214:217], v[78:81]
	v_mfma_f32_16x16x32_bf16 v[110:113], v[134:137], v[214:217], v[110:113]
	v_mfma_f32_16x16x32_bf16 v[26:29], v[146:149], v[162:165], v[26:29]
	v_mfma_f32_16x16x32_bf16 v[2:5], v[154:157], v[162:165], v[2:5]
	v_mfma_f32_16x16x32_bf16 v[6:9], v[154:157], v[170:173], v[6:9]
	v_mfma_f32_16x16x32_bf16 v[34:37], v[146:149], v[170:173], v[34:37]
	v_mfma_f32_16x16x32_bf16 v[38:41], v[146:149], v[202:205], v[38:41]
	v_mfma_f32_16x16x32_bf16 v[10:13], v[154:157], v[202:205], v[10:13]
	v_mfma_f32_16x16x32_bf16 v[14:17], v[154:157], v[210:213], v[14:17]
	v_mfma_f32_16x16x32_bf16 v[46:49], v[146:149], v[210:213], v[46:49]
	v_mfma_f32_16x16x32_bf16 v[26:29], v[150:153], v[166:169], v[26:29]
	v_mfma_f32_16x16x32_bf16 v[2:5], v[158:161], v[166:169], v[2:5]
	v_mfma_f32_16x16x32_bf16 v[6:9], v[158:161], v[174:177], v[6:9]
	v_mfma_f32_16x16x32_bf16 v[34:37], v[150:153], v[174:177], v[34:37]
	v_mfma_f32_16x16x32_bf16 v[38:41], v[150:153], v[206:209], v[38:41]
	v_mfma_f32_16x16x32_bf16 v[10:13], v[158:161], v[206:209], v[10:13]
	v_mfma_f32_16x16x32_bf16 v[14:17], v[158:161], v[214:217], v[14:17]
	v_mfma_f32_16x16x32_bf16 v[46:49], v[150:153], v[214:217], v[46:49]
	s_barrier
	s_setprio 0
	s_add_i32 s18, s27, s15
	v_lshl_add_u64 v[218:219], v[218:219], 0, s[44:45]
	s_mov_b32 m0, s18
	ds_read_b128 v[162:165], v233 offset:49152
	ds_read_b128 v[166:169], v233 offset:50176
	ds_read_b128 v[170:173], v233 offset:51200
	ds_read_b128 v[174:177], v233 offset:52224
	ds_read_b128 v[202:205], v233 offset:53248
	ds_read_b128 v[206:209], v233 offset:54272
	ds_read_b128 v[210:213], v233 offset:55296
	ds_read_b128 v[214:217], v233 offset:56320
	global_load_lds_dwordx4 v[218:219], off
	s_add_i32 m0, s18, 0x2000
	s_add_u32 s16, s16, 0x100080
	v_lshl_add_u64 v[218:219], v[242:243], 0, s[44:45]
	s_addc_u32 s17, s17, 0
	s_add_i32 s18, s59, s15
	global_load_lds_dwordx4 v[218:219], off
	v_lshl_add_u64 v[218:219], s[16:17], 0, v[178:179]
	s_mov_b32 m0, s18
	s_nop 0
	global_load_lds_dwordx4 v[218:219], off
	v_lshl_add_u64 v[218:219], s[16:17], 0, v[180:181]
	s_add_i32 m0, s18, 0x2000
	s_nop 0
	global_load_lds_dwordx4 v[218:219], off
	v_lshl_add_u64 v[218:219], v[244:245], 0, s[44:45]
	s_mov_b32 m0, s66
	s_nop 0
	global_load_lds_dwordx4 v[218:219], off
	v_lshl_add_u64 v[218:219], v[246:247], 0, s[44:45]
	s_mov_b32 m0, s67
	s_nop 0
	global_load_lds_dwordx4 v[218:219], off
	s_waitcnt vmcnt(8)
	s_waitcnt lgkmcnt(0)
	s_setprio 1
	s_barrier
	v_mfma_f32_16x16x32_bf16 v[114:117], v[130:133], v[162:165], v[114:117]
	v_mfma_f32_16x16x32_bf16 v[82:85], v[138:141], v[162:165], v[82:85]
	v_mfma_f32_16x16x32_bf16 v[86:89], v[138:141], v[170:173], v[86:89]
	v_mfma_f32_16x16x32_bf16 v[118:121], v[130:133], v[170:173], v[118:121]
	v_mfma_f32_16x16x32_bf16 v[122:125], v[130:133], v[202:205], v[122:125]
	v_mfma_f32_16x16x32_bf16 v[94:97], v[138:141], v[202:205], v[94:97]
	v_mfma_f32_16x16x32_bf16 v[106:109], v[138:141], v[210:213], v[106:109]
	v_mfma_f32_16x16x32_bf16 v[126:129], v[130:133], v[210:213], v[126:129]
	v_mfma_f32_16x16x32_bf16 v[114:117], v[134:137], v[166:169], v[114:117]
	v_mfma_f32_16x16x32_bf16 v[82:85], v[142:145], v[166:169], v[82:85]
	v_mfma_f32_16x16x32_bf16 v[86:89], v[142:145], v[174:177], v[86:89]
	v_mfma_f32_16x16x32_bf16 v[118:121], v[134:137], v[174:177], v[118:121]
	v_mfma_f32_16x16x32_bf16 v[122:125], v[134:137], v[206:209], v[122:125]
	v_mfma_f32_16x16x32_bf16 v[94:97], v[142:145], v[206:209], v[94:97]
	v_mfma_f32_16x16x32_bf16 v[106:109], v[142:145], v[214:217], v[106:109]
	v_mfma_f32_16x16x32_bf16 v[126:129], v[134:137], v[214:217], v[126:129]
	v_mfma_f32_16x16x32_bf16 v[50:53], v[146:149], v[162:165], v[50:53]
	v_mfma_f32_16x16x32_bf16 v[18:21], v[154:157], v[162:165], v[18:21]
	v_mfma_f32_16x16x32_bf16 v[22:25], v[154:157], v[170:173], v[22:25]
	v_mfma_f32_16x16x32_bf16 v[54:57], v[146:149], v[170:173], v[54:57]
	v_mfma_f32_16x16x32_bf16 v[62:65], v[146:149], v[202:205], v[62:65]
	v_mfma_f32_16x16x32_bf16 v[30:33], v[154:157], v[202:205], v[30:33]
	v_mfma_f32_16x16x32_bf16 v[42:45], v[154:157], v[210:213], v[42:45]
	v_mfma_f32_16x16x32_bf16 v[74:77], v[146:149], v[210:213], v[74:77]
	v_mfma_f32_16x16x32_bf16 v[50:53], v[150:153], v[166:169], v[50:53]
	v_mfma_f32_16x16x32_bf16 v[18:21], v[158:161], v[166:169], v[18:21]
	v_mfma_f32_16x16x32_bf16 v[22:25], v[158:161], v[174:177], v[22:25]
	v_mfma_f32_16x16x32_bf16 v[54:57], v[150:153], v[174:177], v[54:57]
	v_mfma_f32_16x16x32_bf16 v[62:65], v[150:153], v[206:209], v[62:65]
	v_mfma_f32_16x16x32_bf16 v[30:33], v[158:161], v[206:209], v[30:33]
	v_mfma_f32_16x16x32_bf16 v[42:45], v[158:161], v[214:217], v[42:45]
	v_mfma_f32_16x16x32_bf16 v[74:77], v[150:153], v[214:217], v[74:77]
	s_barrier
	s_setprio 0
	s_add_i32 s26, s26, 2
	s_add_u32 s0, s0, 0x100
	s_addc_u32 s1, s1, 0
	s_add_u32 s24, s24, 0x100
	s_addc_u32 s25, s25, 0
.LBB0_672:
	v_add_u32_e32 v142, s51, v220
	v_add_u32_e32 v158, s81, v220
	ds_read_b128 v[130:133], v142
	ds_read_b128 v[134:137], v142 offset:1024
	ds_read_b128 v[138:141], v142 offset:2048
	ds_read_b128 v[142:145], v142 offset:3072
	ds_read_b128 v[146:149], v158
	ds_read_b128 v[150:153], v158 offset:1024
	ds_read_b128 v[154:157], v158 offset:2048
	ds_read_b128 v[158:161], v158 offset:3072
	s_add_u32 s16, s0, 0xfff00080
	s_addc_u32 s17, s1, -1
	s_cmp_eq_u32 s26, 60
	s_cselect_b32 s19, s20, s17
	s_cselect_b32 s18, s21, s16
	s_cselect_b32 s17, s22, s25
	s_cselect_b32 s16, s23, s24
	v_lshl_add_u64 v[218:219], s[0:1], 0, v[194:195]
	s_add_i32 m0, s31, 0xc000
	ds_read_b128 v[162:165], v233
	ds_read_b128 v[166:169], v233 offset:1024
	ds_read_b128 v[170:173], v233 offset:2048
	ds_read_b128 v[174:177], v233 offset:3072
	ds_read_b128 v[202:205], v233 offset:4096
	ds_read_b128 v[206:209], v233 offset:5120
	ds_read_b128 v[210:213], v233 offset:6144
	ds_read_b128 v[214:217], v233 offset:7168
	global_load_lds_dwordx4 v[218:219], off
	v_lshl_add_u64 v[218:219], s[0:1], 0, v[196:197]
	s_add_i32 m0, s31, 0xe000
	s_nop 0
	global_load_lds_dwordx4 v[218:219], off
	s_waitcnt vmcnt(8)
	s_waitcnt lgkmcnt(0)
	s_setprio 1
	s_barrier
	v_mfma_f32_16x16x32_bf16 v[90:93], v[130:133], v[162:165], v[90:93]
	v_mfma_f32_16x16x32_bf16 v[58:61], v[138:141], v[162:165], v[58:61]
	v_mfma_f32_16x16x32_bf16 v[66:69], v[138:141], v[170:173], v[66:69]
	v_mfma_f32_16x16x32_bf16 v[98:101], v[130:133], v[170:173], v[98:101]
	v_mfma_f32_16x16x32_bf16 v[102:105], v[130:133], v[202:205], v[102:105]
	v_mfma_f32_16x16x32_bf16 v[70:73], v[138:141], v[202:205], v[70:73]
	v_mfma_f32_16x16x32_bf16 v[78:81], v[138:141], v[210:213], v[78:81]
	v_mfma_f32_16x16x32_bf16 v[110:113], v[130:133], v[210:213], v[110:113]
	v_mfma_f32_16x16x32_bf16 v[90:93], v[134:137], v[166:169], v[90:93]
	v_mfma_f32_16x16x32_bf16 v[58:61], v[142:145], v[166:169], v[58:61]
	v_mfma_f32_16x16x32_bf16 v[66:69], v[142:145], v[174:177], v[66:69]
	v_mfma_f32_16x16x32_bf16 v[98:101], v[134:137], v[174:177], v[98:101]
	v_mfma_f32_16x16x32_bf16 v[102:105], v[134:137], v[206:209], v[102:105]
	v_mfma_f32_16x16x32_bf16 v[70:73], v[142:145], v[206:209], v[70:73]
	v_mfma_f32_16x16x32_bf16 v[78:81], v[142:145], v[214:217], v[78:81]
	v_mfma_f32_16x16x32_bf16 v[110:113], v[134:137], v[214:217], v[110:113]
	v_mfma_f32_16x16x32_bf16 v[26:29], v[146:149], v[162:165], v[26:29]
	v_mfma_f32_16x16x32_bf16 v[2:5], v[154:157], v[162:165], v[2:5]
	v_mfma_f32_16x16x32_bf16 v[6:9], v[154:157], v[170:173], v[6:9]
	v_mfma_f32_16x16x32_bf16 v[34:37], v[146:149], v[170:173], v[34:37]
	v_mfma_f32_16x16x32_bf16 v[38:41], v[146:149], v[202:205], v[38:41]
	v_mfma_f32_16x16x32_bf16 v[10:13], v[154:157], v[202:205], v[10:13]
	v_mfma_f32_16x16x32_bf16 v[14:17], v[154:157], v[210:213], v[14:17]
	v_mfma_f32_16x16x32_bf16 v[46:49], v[146:149], v[210:213], v[46:49]
	v_mfma_f32_16x16x32_bf16 v[26:29], v[150:153], v[166:169], v[26:29]
	v_mfma_f32_16x16x32_bf16 v[2:5], v[158:161], v[166:169], v[2:5]
	v_mfma_f32_16x16x32_bf16 v[6:9], v[158:161], v[174:177], v[6:9]
	v_mfma_f32_16x16x32_bf16 v[34:37], v[150:153], v[174:177], v[34:37]
	v_mfma_f32_16x16x32_bf16 v[38:41], v[150:153], v[206:209], v[38:41]
	v_mfma_f32_16x16x32_bf16 v[10:13], v[158:161], v[206:209], v[10:13]
	v_mfma_f32_16x16x32_bf16 v[14:17], v[158:161], v[214:217], v[14:17]
	v_mfma_f32_16x16x32_bf16 v[46:49], v[150:153], v[214:217], v[46:49]
	s_barrier
	s_setprio 0
	s_add_i32 s27, s51, s15
	v_lshl_add_u64 v[218:219], s[16:17], 0, v[178:179]
	s_mov_b32 m0, s27
	ds_read_b128 v[162:165], v233 offset:16384
	ds_read_b128 v[166:169], v233 offset:17408
	ds_read_b128 v[170:173], v233 offset:18432
	ds_read_b128 v[174:177], v233 offset:19456
	ds_read_b128 v[202:205], v233 offset:20480
	ds_read_b128 v[206:209], v233 offset:21504
	ds_read_b128 v[210:213], v233 offset:22528
	ds_read_b128 v[214:217], v233 offset:23552
	global_load_lds_dwordx4 v[218:219], off
	s_add_i32 m0, s27, 0x2000
	s_add_u32 s62, s16, 0x100000
	v_lshl_add_u64 v[242:243], s[16:17], 0, v[180:181]
	s_addc_u32 s63, s17, 0
	s_add_i32 s27, s81, s15
	global_load_lds_dwordx4 v[242:243], off
	v_lshl_add_u64 v[244:245], s[62:63], 0, v[178:179]
	s_mov_b32 m0, s27
	v_lshl_add_u64 v[246:247], s[18:19], 0, v[180:181]
	global_load_lds_dwordx4 v[244:245], off
	v_lshl_add_u64 v[244:245], s[62:63], 0, v[180:181]
	s_add_i32 m0, s27, 0x2000
	s_nop 0
	global_load_lds_dwordx4 v[244:245], off
	v_lshl_add_u64 v[244:245], s[18:19], 0, v[178:179]
	s_mov_b32 m0, s31
	s_nop 0
	global_load_lds_dwordx4 v[244:245], off
	s_mov_b32 m0, s34
	s_nop 0
	global_load_lds_dwordx4 v[246:247], off
	s_waitcnt vmcnt(8)
	s_waitcnt lgkmcnt(0)
	s_setprio 1
	s_barrier
	v_mfma_f32_16x16x32_bf16 v[114:117], v[130:133], v[162:165], v[114:117]
	v_mfma_f32_16x16x32_bf16 v[82:85], v[138:141], v[162:165], v[82:85]
	v_mfma_f32_16x16x32_bf16 v[86:89], v[138:141], v[170:173], v[86:89]
	v_mfma_f32_16x16x32_bf16 v[118:121], v[130:133], v[170:173], v[118:121]
	v_mfma_f32_16x16x32_bf16 v[122:125], v[130:133], v[202:205], v[122:125]
	v_mfma_f32_16x16x32_bf16 v[94:97], v[138:141], v[202:205], v[94:97]
	v_mfma_f32_16x16x32_bf16 v[106:109], v[138:141], v[210:213], v[106:109]
	v_mfma_f32_16x16x32_bf16 v[126:129], v[130:133], v[210:213], v[126:129]
	v_mfma_f32_16x16x32_bf16 v[114:117], v[134:137], v[166:169], v[114:117]
	v_mfma_f32_16x16x32_bf16 v[82:85], v[142:145], v[166:169], v[82:85]
	v_mfma_f32_16x16x32_bf16 v[86:89], v[142:145], v[174:177], v[86:89]
	v_mfma_f32_16x16x32_bf16 v[118:121], v[134:137], v[174:177], v[118:121]
	v_mfma_f32_16x16x32_bf16 v[122:125], v[134:137], v[206:209], v[122:125]
	v_mfma_f32_16x16x32_bf16 v[94:97], v[142:145], v[206:209], v[94:97]
	v_mfma_f32_16x16x32_bf16 v[106:109], v[142:145], v[214:217], v[106:109]
	v_mfma_f32_16x16x32_bf16 v[126:129], v[134:137], v[214:217], v[126:129]
	v_mfma_f32_16x16x32_bf16 v[50:53], v[146:149], v[162:165], v[50:53]
	v_mfma_f32_16x16x32_bf16 v[18:21], v[154:157], v[162:165], v[18:21]
	v_mfma_f32_16x16x32_bf16 v[22:25], v[154:157], v[170:173], v[22:25]
	v_mfma_f32_16x16x32_bf16 v[54:57], v[146:149], v[170:173], v[54:57]
	v_mfma_f32_16x16x32_bf16 v[62:65], v[146:149], v[202:205], v[62:65]
	v_mfma_f32_16x16x32_bf16 v[30:33], v[154:157], v[202:205], v[30:33]
	v_mfma_f32_16x16x32_bf16 v[42:45], v[154:157], v[210:213], v[42:45]
	v_mfma_f32_16x16x32_bf16 v[74:77], v[146:149], v[210:213], v[74:77]
	v_mfma_f32_16x16x32_bf16 v[50:53], v[150:153], v[166:169], v[50:53]
	v_mfma_f32_16x16x32_bf16 v[18:21], v[158:161], v[166:169], v[18:21]
	v_mfma_f32_16x16x32_bf16 v[22:25], v[158:161], v[174:177], v[22:25]
	v_mfma_f32_16x16x32_bf16 v[54:57], v[150:153], v[174:177], v[54:57]
	v_mfma_f32_16x16x32_bf16 v[62:65], v[150:153], v[206:209], v[62:65]
	v_mfma_f32_16x16x32_bf16 v[30:33], v[158:161], v[206:209], v[30:33]
	v_mfma_f32_16x16x32_bf16 v[42:45], v[158:161], v[214:217], v[42:45]
	v_mfma_f32_16x16x32_bf16 v[74:77], v[150:153], v[214:217], v[74:77]
	s_barrier
	s_setprio 0
	s_add_i32 s27, 0, 0x18000
	s_add_i32 s59, 0, 0x1c000
	v_add_u32_e32 v142, s27, v220
	v_add_u32_e32 v158, s59, v220
	ds_read_b128 v[130:133], v142
	ds_read_b128 v[134:137], v142 offset:1024
	ds_read_b128 v[138:141], v142 offset:2048
	ds_read_b128 v[142:145], v142 offset:3072
	ds_read_b128 v[146:149], v158
	ds_read_b128 v[150:153], v158 offset:1024
	ds_read_b128 v[154:157], v158 offset:2048
	ds_read_b128 v[158:161], v158 offset:3072
	s_add_u32 s18, s18, 0x100000
	s_addc_u32 s19, s19, 0
	s_mov_b32 m0, s35
	v_lshl_add_u64 v[248:249], s[18:19], 0, v[178:179]
	ds_read_b128 v[162:165], v233 offset:32768
	ds_read_b128 v[166:169], v233 offset:33792
	ds_read_b128 v[170:173], v233 offset:34816
	ds_read_b128 v[174:177], v233 offset:35840
	ds_read_b128 v[202:205], v233 offset:36864
	ds_read_b128 v[206:209], v233 offset:37888
	ds_read_b128 v[210:213], v233 offset:38912
	ds_read_b128 v[214:217], v233 offset:39936
	global_load_lds_dwordx4 v[248:249], off
	v_lshl_add_u64 v[248:249], s[18:19], 0, v[180:181]
	s_mov_b32 m0, s86
	s_nop 0
	global_load_lds_dwordx4 v[248:249], off
	s_waitcnt vmcnt(8)
	s_waitcnt lgkmcnt(0)
	s_setprio 1
	s_barrier
	v_mfma_f32_16x16x32_bf16 v[90:93], v[130:133], v[162:165], v[90:93]
	v_mfma_f32_16x16x32_bf16 v[58:61], v[138:141], v[162:165], v[58:61]
	v_mfma_f32_16x16x32_bf16 v[66:69], v[138:141], v[170:173], v[66:69]
	v_mfma_f32_16x16x32_bf16 v[98:101], v[130:133], v[170:173], v[98:101]
	v_mfma_f32_16x16x32_bf16 v[102:105], v[130:133], v[202:205], v[102:105]
	v_mfma_f32_16x16x32_bf16 v[70:73], v[138:141], v[202:205], v[70:73]
	v_mfma_f32_16x16x32_bf16 v[78:81], v[138:141], v[210:213], v[78:81]
	v_mfma_f32_16x16x32_bf16 v[110:113], v[130:133], v[210:213], v[110:113]
	v_mfma_f32_16x16x32_bf16 v[90:93], v[134:137], v[166:169], v[90:93]
	v_mfma_f32_16x16x32_bf16 v[58:61], v[142:145], v[166:169], v[58:61]
	v_mfma_f32_16x16x32_bf16 v[66:69], v[142:145], v[174:177], v[66:69]
	v_mfma_f32_16x16x32_bf16 v[98:101], v[134:137], v[174:177], v[98:101]
	v_mfma_f32_16x16x32_bf16 v[102:105], v[134:137], v[206:209], v[102:105]
	v_mfma_f32_16x16x32_bf16 v[70:73], v[142:145], v[206:209], v[70:73]
	v_mfma_f32_16x16x32_bf16 v[78:81], v[142:145], v[214:217], v[78:81]
	v_mfma_f32_16x16x32_bf16 v[110:113], v[134:137], v[214:217], v[110:113]
	v_mfma_f32_16x16x32_bf16 v[26:29], v[146:149], v[162:165], v[26:29]
	v_mfma_f32_16x16x32_bf16 v[2:5], v[154:157], v[162:165], v[2:5]
	v_mfma_f32_16x16x32_bf16 v[6:9], v[154:157], v[170:173], v[6:9]
	v_mfma_f32_16x16x32_bf16 v[34:37], v[146:149], v[170:173], v[34:37]
	v_mfma_f32_16x16x32_bf16 v[38:41], v[146:149], v[202:205], v[38:41]
	v_mfma_f32_16x16x32_bf16 v[10:13], v[154:157], v[202:205], v[10:13]
	v_mfma_f32_16x16x32_bf16 v[14:17], v[154:157], v[210:213], v[14:17]
	v_mfma_f32_16x16x32_bf16 v[46:49], v[146:149], v[210:213], v[46:49]
	v_mfma_f32_16x16x32_bf16 v[26:29], v[150:153], v[166:169], v[26:29]
	v_mfma_f32_16x16x32_bf16 v[2:5], v[158:161], v[166:169], v[2:5]
	v_mfma_f32_16x16x32_bf16 v[6:9], v[158:161], v[174:177], v[6:9]
	v_mfma_f32_16x16x32_bf16 v[34:37], v[150:153], v[174:177], v[34:37]
	v_mfma_f32_16x16x32_bf16 v[38:41], v[150:153], v[206:209], v[38:41]
	v_mfma_f32_16x16x32_bf16 v[10:13], v[158:161], v[206:209], v[10:13]
	v_mfma_f32_16x16x32_bf16 v[14:17], v[158:161], v[214:217], v[14:17]
	v_mfma_f32_16x16x32_bf16 v[46:49], v[150:153], v[214:217], v[46:49]
	s_barrier
	s_setprio 0
	s_add_i32 s18, s27, s15
	v_lshl_add_u64 v[218:219], v[218:219], 0, s[44:45]
	s_mov_b32 m0, s18
	ds_read_b128 v[162:165], v233 offset:49152
	ds_read_b128 v[166:169], v233 offset:50176
	ds_read_b128 v[170:173], v233 offset:51200
	ds_read_b128 v[174:177], v233 offset:52224
	ds_read_b128 v[202:205], v233 offset:53248
	ds_read_b128 v[206:209], v233 offset:54272
	ds_read_b128 v[210:213], v233 offset:55296
	ds_read_b128 v[214:217], v233 offset:56320
	global_load_lds_dwordx4 v[218:219], off
	s_add_i32 m0, s18, 0x2000
	s_add_u32 s16, s16, 0x100080
	v_lshl_add_u64 v[218:219], v[242:243], 0, s[44:45]
	s_addc_u32 s17, s17, 0
	s_add_i32 s18, s59, s15
	global_load_lds_dwordx4 v[218:219], off
	v_lshl_add_u64 v[218:219], s[16:17], 0, v[178:179]
	s_mov_b32 m0, s18
	s_nop 0
	global_load_lds_dwordx4 v[218:219], off
	v_lshl_add_u64 v[218:219], s[16:17], 0, v[180:181]
	s_add_i32 m0, s18, 0x2000
	s_nop 0
	global_load_lds_dwordx4 v[218:219], off
	v_lshl_add_u64 v[218:219], v[244:245], 0, s[44:45]
	s_mov_b32 m0, s66
	s_nop 0
	global_load_lds_dwordx4 v[218:219], off
	v_lshl_add_u64 v[218:219], v[246:247], 0, s[44:45]
	s_mov_b32 m0, s67
	s_nop 0
	global_load_lds_dwordx4 v[218:219], off
	s_waitcnt vmcnt(8)
	s_waitcnt lgkmcnt(0)
	s_setprio 1
	s_barrier
	v_mfma_f32_16x16x32_bf16 v[114:117], v[130:133], v[162:165], v[114:117]
	v_mfma_f32_16x16x32_bf16 v[82:85], v[138:141], v[162:165], v[82:85]
	v_mfma_f32_16x16x32_bf16 v[86:89], v[138:141], v[170:173], v[86:89]
	v_mfma_f32_16x16x32_bf16 v[118:121], v[130:133], v[170:173], v[118:121]
	v_mfma_f32_16x16x32_bf16 v[122:125], v[130:133], v[202:205], v[122:125]
	v_mfma_f32_16x16x32_bf16 v[94:97], v[138:141], v[202:205], v[94:97]
	v_mfma_f32_16x16x32_bf16 v[106:109], v[138:141], v[210:213], v[106:109]
	v_mfma_f32_16x16x32_bf16 v[126:129], v[130:133], v[210:213], v[126:129]
	v_mfma_f32_16x16x32_bf16 v[114:117], v[134:137], v[166:169], v[114:117]
	v_mfma_f32_16x16x32_bf16 v[82:85], v[142:145], v[166:169], v[82:85]
	v_mfma_f32_16x16x32_bf16 v[86:89], v[142:145], v[174:177], v[86:89]
	v_mfma_f32_16x16x32_bf16 v[118:121], v[134:137], v[174:177], v[118:121]
	v_mfma_f32_16x16x32_bf16 v[122:125], v[134:137], v[206:209], v[122:125]
	v_mfma_f32_16x16x32_bf16 v[94:97], v[142:145], v[206:209], v[94:97]
	v_mfma_f32_16x16x32_bf16 v[106:109], v[142:145], v[214:217], v[106:109]
	v_mfma_f32_16x16x32_bf16 v[126:129], v[134:137], v[214:217], v[126:129]
	v_mfma_f32_16x16x32_bf16 v[50:53], v[146:149], v[162:165], v[50:53]
	v_mfma_f32_16x16x32_bf16 v[18:21], v[154:157], v[162:165], v[18:21]
	v_mfma_f32_16x16x32_bf16 v[22:25], v[154:157], v[170:173], v[22:25]
	v_mfma_f32_16x16x32_bf16 v[54:57], v[146:149], v[170:173], v[54:57]
	v_mfma_f32_16x16x32_bf16 v[62:65], v[146:149], v[202:205], v[62:65]
	v_mfma_f32_16x16x32_bf16 v[30:33], v[154:157], v[202:205], v[30:33]
	v_mfma_f32_16x16x32_bf16 v[42:45], v[154:157], v[210:213], v[42:45]
	v_mfma_f32_16x16x32_bf16 v[74:77], v[146:149], v[210:213], v[74:77]
	v_mfma_f32_16x16x32_bf16 v[50:53], v[150:153], v[166:169], v[50:53]
	v_mfma_f32_16x16x32_bf16 v[18:21], v[158:161], v[166:169], v[18:21]
	v_mfma_f32_16x16x32_bf16 v[22:25], v[158:161], v[174:177], v[22:25]
	v_mfma_f32_16x16x32_bf16 v[54:57], v[150:153], v[174:177], v[54:57]
	v_mfma_f32_16x16x32_bf16 v[62:65], v[150:153], v[206:209], v[62:65]
	v_mfma_f32_16x16x32_bf16 v[30:33], v[158:161], v[206:209], v[30:33]
	v_mfma_f32_16x16x32_bf16 v[42:45], v[158:161], v[214:217], v[42:45]
	v_mfma_f32_16x16x32_bf16 v[74:77], v[150:153], v[214:217], v[74:77]
	s_barrier
	s_setprio 0
	s_add_i32 s26, s26, 2
	s_add_u32 s0, s0, 0x100
	s_addc_u32 s1, s1, 0
	s_add_u32 s24, s24, 0x100
	s_addc_u32 s25, s25, 0
	s_cmp_gt_u32 s26, 61
	s_cbranch_scc0 .LBB0_672
	s_and_b64 vcc, exec, s[90:91]
	s_cbranch_vccz .LBB0_675
	s_barrier

.Lpeelc:
	ds_read_b128 v[156:159], v153
	ds_read_b128 v[160:163], v153 offset:1024
	ds_read_b128 v[164:167], v153 offset:2048
	ds_read_b128 v[168:171], v153 offset:3072
	ds_read_b128 v[172:175], v154
	ds_read_b128 v[176:179], v154 offset:1024
	ds_read_b128 v[180:183], v154 offset:2048
	ds_read_b128 v[184:187], v154 offset:3072
	s_add_u32 s36, s26, 0xfff00080
	s_addc_u32 s37, s27, -1
	s_cmp_eq_u32 s54, 60
	s_cselect_b32 s39, s19, s37
	s_cselect_b32 s38, s50, s36
	s_cselect_b32 s37, s17, s53
	s_cselect_b32 s36, s51, s52
	v_lshl_add_u64 v[148:149], s[26:27], 0, v[140:141]
	s_add_i32 m0, s25, 0xc000
	ds_read_b128 v[188:191], v155
	ds_read_b128 v[192:195], v155 offset:1024
	ds_read_b128 v[196:199], v155 offset:2048
	ds_read_b128 v[200:203], v155 offset:3072
	ds_read_b128 v[204:207], v155 offset:4096
	ds_read_b128 v[208:211], v155 offset:5120
	ds_read_b128 v[212:215], v155 offset:6144
	ds_read_b128 v[216:219], v155 offset:7168
	global_load_lds_dwordx4 v[148:149], off
	v_lshl_add_u64 v[148:149], s[26:27], 0, v[142:143]
	s_add_i32 m0, s25, 0xe000
	s_nop 0
	global_load_lds_dwordx4 v[148:149], off
	s_waitcnt vmcnt(8)
	s_waitcnt lgkmcnt(0)
	s_setprio 1
	s_barrier
	v_mfma_f32_16x16x32_bf16 v[126:129], v[156:159], v[188:191], 0
	v_mfma_f32_16x16x32_bf16 v[122:125], v[164:167], v[188:191], 0
	v_mfma_f32_16x16x32_bf16 v[114:117], v[164:167], v[196:199], 0
	v_mfma_f32_16x16x32_bf16 v[118:121], v[156:159], v[196:199], 0
	v_mfma_f32_16x16x32_bf16 v[94:97], v[156:159], v[204:207], 0
	v_mfma_f32_16x16x32_bf16 v[90:93], v[164:167], v[204:207], 0
	v_mfma_f32_16x16x32_bf16 v[82:85], v[164:167], v[212:215], 0
	v_mfma_f32_16x16x32_bf16 v[86:89], v[156:159], v[212:215], 0
	v_mfma_f32_16x16x32_bf16 v[126:129], v[160:163], v[192:195], v[126:129]
	v_mfma_f32_16x16x32_bf16 v[122:125], v[168:171], v[192:195], v[122:125]
	v_mfma_f32_16x16x32_bf16 v[114:117], v[168:171], v[200:203], v[114:117]
	v_mfma_f32_16x16x32_bf16 v[118:121], v[160:163], v[200:203], v[118:121]
	v_mfma_f32_16x16x32_bf16 v[94:97], v[160:163], v[208:211], v[94:97]
	v_mfma_f32_16x16x32_bf16 v[90:93], v[168:171], v[208:211], v[90:93]
	v_mfma_f32_16x16x32_bf16 v[82:85], v[168:171], v[216:219], v[82:85]
	v_mfma_f32_16x16x32_bf16 v[86:89], v[160:163], v[216:219], v[86:89]
	v_mfma_f32_16x16x32_bf16 v[110:113], v[172:175], v[188:191], 0
	v_mfma_f32_16x16x32_bf16 v[106:109], v[180:183], v[188:191], 0
	v_mfma_f32_16x16x32_bf16 v[98:101], v[180:183], v[196:199], 0
	v_mfma_f32_16x16x32_bf16 v[102:105], v[172:175], v[196:199], 0
	v_mfma_f32_16x16x32_bf16 v[78:81], v[172:175], v[204:207], 0
	v_mfma_f32_16x16x32_bf16 v[74:77], v[180:183], v[204:207], 0
	v_mfma_f32_16x16x32_bf16 v[66:69], v[180:183], v[212:215], 0
	v_mfma_f32_16x16x32_bf16 v[70:73], v[172:175], v[212:215], 0
	v_mfma_f32_16x16x32_bf16 v[110:113], v[176:179], v[192:195], v[110:113]
	v_mfma_f32_16x16x32_bf16 v[106:109], v[184:187], v[192:195], v[106:109]
	v_mfma_f32_16x16x32_bf16 v[98:101], v[184:187], v[200:203], v[98:101]
	v_mfma_f32_16x16x32_bf16 v[102:105], v[176:179], v[200:203], v[102:105]
	v_mfma_f32_16x16x32_bf16 v[78:81], v[176:179], v[208:211], v[78:81]
	v_mfma_f32_16x16x32_bf16 v[74:77], v[184:187], v[208:211], v[74:77]
	v_mfma_f32_16x16x32_bf16 v[66:69], v[184:187], v[216:219], v[66:69]
	v_mfma_f32_16x16x32_bf16 v[70:73], v[176:179], v[216:219], v[70:73]
	s_barrier
	s_setprio 0
	s_add_i32 s55, s44, s13
	v_lshl_add_u64 v[148:149], s[36:37], 0, v[134:135]
	s_mov_b32 m0, s55
	ds_read_b128 v[188:191], v155 offset:16384
	ds_read_b128 v[192:195], v155 offset:17408
	ds_read_b128 v[196:199], v155 offset:18432
	ds_read_b128 v[200:203], v155 offset:19456
	ds_read_b128 v[204:207], v155 offset:20480
	ds_read_b128 v[208:211], v155 offset:21504
	ds_read_b128 v[212:215], v155 offset:22528
	ds_read_b128 v[216:219], v155 offset:23552
	global_load_lds_dwordx4 v[148:149], off
	s_add_i32 m0, s55, 0x2000
	s_add_u32 s56, s36, 0x100000
	v_lshl_add_u64 v[220:221], s[36:37], 0, v[130:131]
	s_addc_u32 s57, s37, 0
	s_add_i32 s55, s45, s13
	global_load_lds_dwordx4 v[220:221], off
	v_lshl_add_u64 v[224:225], s[56:57], 0, v[134:135]
	s_mov_b32 m0, s55
	v_lshl_add_u64 v[226:227], s[38:39], 0, v[132:133]
	global_load_lds_dwordx4 v[224:225], off
	v_lshl_add_u64 v[224:225], s[56:57], 0, v[130:131]
	s_add_i32 m0, s55, 0x2000
	s_nop 0
	global_load_lds_dwordx4 v[224:225], off
	v_lshl_add_u64 v[224:225], s[38:39], 0, v[136:137]
	s_mov_b32 m0, s25
	s_nop 0
	global_load_lds_dwordx4 v[224:225], off
	s_mov_b32 m0, s31
	s_nop 0
	global_load_lds_dwordx4 v[226:227], off
	s_waitcnt vmcnt(8)
	s_waitcnt lgkmcnt(0)
	s_setprio 1
	s_barrier
	v_mfma_f32_16x16x32_bf16 v[62:65], v[156:159], v[188:191], 0
	v_mfma_f32_16x16x32_bf16 v[58:61], v[164:167], v[188:191], 0
	v_mfma_f32_16x16x32_bf16 v[50:53], v[164:167], v[196:199], 0
	v_mfma_f32_16x16x32_bf16 v[54:57], v[156:159], v[196:199], 0
	v_mfma_f32_16x16x32_bf16 v[30:33], v[156:159], v[204:207], 0
	v_mfma_f32_16x16x32_bf16 v[26:29], v[164:167], v[204:207], 0
	v_mfma_f32_16x16x32_bf16 v[18:21], v[164:167], v[212:215], 0
	v_mfma_f32_16x16x32_bf16 v[22:25], v[156:159], v[212:215], 0
	v_mfma_f32_16x16x32_bf16 v[62:65], v[160:163], v[192:195], v[62:65]
	v_mfma_f32_16x16x32_bf16 v[58:61], v[168:171], v[192:195], v[58:61]
	v_mfma_f32_16x16x32_bf16 v[50:53], v[168:171], v[200:203], v[50:53]
	v_mfma_f32_16x16x32_bf16 v[54:57], v[160:163], v[200:203], v[54:57]
	v_mfma_f32_16x16x32_bf16 v[30:33], v[160:163], v[208:211], v[30:33]
	v_mfma_f32_16x16x32_bf16 v[26:29], v[168:171], v[208:211], v[26:29]
	v_mfma_f32_16x16x32_bf16 v[18:21], v[168:171], v[216:219], v[18:21]
	v_mfma_f32_16x16x32_bf16 v[22:25], v[160:163], v[216:219], v[22:25]
	v_mfma_f32_16x16x32_bf16 v[46:49], v[172:175], v[188:191], 0
	v_mfma_f32_16x16x32_bf16 v[42:45], v[180:183], v[188:191], 0
	v_mfma_f32_16x16x32_bf16 v[34:37], v[180:183], v[196:199], 0
	v_mfma_f32_16x16x32_bf16 v[38:41], v[172:175], v[196:199], 0
	v_mfma_f32_16x16x32_bf16 v[14:17], v[172:175], v[204:207], 0
	v_mfma_f32_16x16x32_bf16 v[10:13], v[180:183], v[204:207], 0
	v_mfma_f32_16x16x32_bf16 v[2:5], v[180:183], v[212:215], 0
	v_mfma_f32_16x16x32_bf16 v[6:9], v[172:175], v[212:215], 0
	v_mfma_f32_16x16x32_bf16 v[46:49], v[176:179], v[192:195], v[46:49]
	v_mfma_f32_16x16x32_bf16 v[42:45], v[184:187], v[192:195], v[42:45]
	v_mfma_f32_16x16x32_bf16 v[34:37], v[184:187], v[200:203], v[34:37]
	v_mfma_f32_16x16x32_bf16 v[38:41], v[176:179], v[200:203], v[38:41]
	v_mfma_f32_16x16x32_bf16 v[14:17], v[176:179], v[208:211], v[14:17]
	v_mfma_f32_16x16x32_bf16 v[10:13], v[184:187], v[208:211], v[10:13]
	v_mfma_f32_16x16x32_bf16 v[2:5], v[184:187], v[216:219], v[2:5]
	v_mfma_f32_16x16x32_bf16 v[6:9], v[176:179], v[216:219], v[6:9]
	s_barrier
	s_setprio 0
	s_add_i32 s55, 0, 0x18000
	s_add_i32 s56, 0, 0x1c000
	v_add_u32_e32 v168, s55, v151
	v_add_u32_e32 v184, s56, v151
	ds_read_b128 v[156:159], v168
	ds_read_b128 v[160:163], v168 offset:1024
	ds_read_b128 v[164:167], v168 offset:2048
	ds_read_b128 v[168:171], v168 offset:3072
	ds_read_b128 v[172:175], v184
	ds_read_b128 v[176:179], v184 offset:1024
	ds_read_b128 v[180:183], v184 offset:2048
	ds_read_b128 v[184:187], v184 offset:3072
	s_add_u32 s38, s38, 0x100000
	s_addc_u32 s39, s39, 0
	s_mov_b32 m0, s34
	v_lshl_add_u64 v[228:229], s[38:39], 0, v[136:137]
	ds_read_b128 v[188:191], v155 offset:32768
	ds_read_b128 v[192:195], v155 offset:33792
	ds_read_b128 v[196:199], v155 offset:34816
	ds_read_b128 v[200:203], v155 offset:35840
	ds_read_b128 v[204:207], v155 offset:36864
	ds_read_b128 v[208:211], v155 offset:37888
	ds_read_b128 v[212:215], v155 offset:38912
	ds_read_b128 v[216:219], v155 offset:39936
	global_load_lds_dwordx4 v[228:229], off
	v_lshl_add_u64 v[228:229], s[38:39], 0, v[132:133]
	s_mov_b32 m0, s35
	s_nop 0
	global_load_lds_dwordx4 v[228:229], off
	s_waitcnt vmcnt(8)
	s_waitcnt lgkmcnt(0)
	s_setprio 1
	s_barrier
	v_mfma_f32_16x16x32_bf16 v[126:129], v[156:159], v[188:191], v[126:129]
	v_mfma_f32_16x16x32_bf16 v[122:125], v[164:167], v[188:191], v[122:125]
	v_mfma_f32_16x16x32_bf16 v[114:117], v[164:167], v[196:199], v[114:117]
	v_mfma_f32_16x16x32_bf16 v[118:121], v[156:159], v[196:199], v[118:121]
	v_mfma_f32_16x16x32_bf16 v[94:97], v[156:159], v[204:207], v[94:97]
	v_mfma_f32_16x16x32_bf16 v[90:93], v[164:167], v[204:207], v[90:93]
	v_mfma_f32_16x16x32_bf16 v[82:85], v[164:167], v[212:215], v[82:85]
	v_mfma_f32_16x16x32_bf16 v[86:89], v[156:159], v[212:215], v[86:89]
	v_mfma_f32_16x16x32_bf16 v[126:129], v[160:163], v[192:195], v[126:129]
	v_mfma_f32_16x16x32_bf16 v[122:125], v[168:171], v[192:195], v[122:125]
	v_mfma_f32_16x16x32_bf16 v[114:117], v[168:171], v[200:203], v[114:117]
	v_mfma_f32_16x16x32_bf16 v[118:121], v[160:163], v[200:203], v[118:121]
	v_mfma_f32_16x16x32_bf16 v[94:97], v[160:163], v[208:211], v[94:97]
	v_mfma_f32_16x16x32_bf16 v[90:93], v[168:171], v[208:211], v[90:93]
	v_mfma_f32_16x16x32_bf16 v[82:85], v[168:171], v[216:219], v[82:85]
	v_mfma_f32_16x16x32_bf16 v[86:89], v[160:163], v[216:219], v[86:89]
	v_mfma_f32_16x16x32_bf16 v[110:113], v[172:175], v[188:191], v[110:113]
	v_mfma_f32_16x16x32_bf16 v[106:109], v[180:183], v[188:191], v[106:109]
	v_mfma_f32_16x16x32_bf16 v[98:101], v[180:183], v[196:199], v[98:101]
	v_mfma_f32_16x16x32_bf16 v[102:105], v[172:175], v[196:199], v[102:105]
	v_mfma_f32_16x16x32_bf16 v[78:81], v[172:175], v[204:207], v[78:81]
	v_mfma_f32_16x16x32_bf16 v[74:77], v[180:183], v[204:207], v[74:77]
	v_mfma_f32_16x16x32_bf16 v[66:69], v[180:183], v[212:215], v[66:69]
	v_mfma_f32_16x16x32_bf16 v[70:73], v[172:175], v[212:215], v[70:73]
	v_mfma_f32_16x16x32_bf16 v[110:113], v[176:179], v[192:195], v[110:113]
	v_mfma_f32_16x16x32_bf16 v[106:109], v[184:187], v[192:195], v[106:109]
	v_mfma_f32_16x16x32_bf16 v[98:101], v[184:187], v[200:203], v[98:101]
	v_mfma_f32_16x16x32_bf16 v[102:105], v[176:179], v[200:203], v[102:105]
	v_mfma_f32_16x16x32_bf16 v[78:81], v[176:179], v[208:211], v[78:81]
	v_mfma_f32_16x16x32_bf16 v[74:77], v[184:187], v[208:211], v[74:77]
	v_mfma_f32_16x16x32_bf16 v[66:69], v[184:187], v[216:219], v[66:69]
	v_mfma_f32_16x16x32_bf16 v[70:73], v[176:179], v[216:219], v[70:73]
	s_barrier
	s_setprio 0
	s_add_i32 s38, s55, s13
	v_lshl_add_u64 v[148:149], v[148:149], 0, s[6:7]
	s_mov_b32 m0, s38
	ds_read_b128 v[188:191], v155 offset:49152
	ds_read_b128 v[192:195], v155 offset:50176
	ds_read_b128 v[196:199], v155 offset:51200
	ds_read_b128 v[200:203], v155 offset:52224
	ds_read_b128 v[204:207], v155 offset:53248
	ds_read_b128 v[208:211], v155 offset:54272
	ds_read_b128 v[212:215], v155 offset:55296
	ds_read_b128 v[216:219], v155 offset:56320
	global_load_lds_dwordx4 v[148:149], off
	s_add_i32 m0, s38, 0x2000
	s_add_u32 s36, s36, 0x100080
	v_lshl_add_u64 v[148:149], v[220:221], 0, s[6:7]
	s_addc_u32 s37, s37, 0
	s_add_i32 s38, s56, s13
	global_load_lds_dwordx4 v[148:149], off
	v_lshl_add_u64 v[148:149], s[36:37], 0, v[134:135]
	s_mov_b32 m0, s38
	s_nop 0
	global_load_lds_dwordx4 v[148:149], off
	v_lshl_add_u64 v[148:149], s[36:37], 0, v[130:131]
	s_add_i32 m0, s38, 0x2000
	s_nop 0
	global_load_lds_dwordx4 v[148:149], off
	v_lshl_add_u64 v[148:149], v[224:225], 0, s[6:7]
	s_mov_b32 m0, s41
	s_nop 0
	global_load_lds_dwordx4 v[148:149], off
	v_lshl_add_u64 v[148:149], v[226:227], 0, s[6:7]
	s_mov_b32 m0, s42
	s_nop 0
	global_load_lds_dwordx4 v[148:149], off
	s_waitcnt vmcnt(8)
	s_waitcnt lgkmcnt(0)
	s_setprio 1
	s_barrier
	v_mfma_f32_16x16x32_bf16 v[62:65], v[156:159], v[188:191], v[62:65]
	v_mfma_f32_16x16x32_bf16 v[58:61], v[164:167], v[188:191], v[58:61]
	v_mfma_f32_16x16x32_bf16 v[50:53], v[164:167], v[196:199], v[50:53]
	v_mfma_f32_16x16x32_bf16 v[54:57], v[156:159], v[196:199], v[54:57]
	v_mfma_f32_16x16x32_bf16 v[30:33], v[156:159], v[204:207], v[30:33]
	v_mfma_f32_16x16x32_bf16 v[26:29], v[164:167], v[204:207], v[26:29]
	v_mfma_f32_16x16x32_bf16 v[18:21], v[164:167], v[212:215], v[18:21]
	v_mfma_f32_16x16x32_bf16 v[22:25], v[156:159], v[212:215], v[22:25]
	v_mfma_f32_16x16x32_bf16 v[62:65], v[160:163], v[192:195], v[62:65]
	v_mfma_f32_16x16x32_bf16 v[58:61], v[168:171], v[192:195], v[58:61]
	v_mfma_f32_16x16x32_bf16 v[50:53], v[168:171], v[200:203], v[50:53]
	v_mfma_f32_16x16x32_bf16 v[54:57], v[160:163], v[200:203], v[54:57]
	v_mfma_f32_16x16x32_bf16 v[30:33], v[160:163], v[208:211], v[30:33]
	v_mfma_f32_16x16x32_bf16 v[26:29], v[168:171], v[208:211], v[26:29]
	v_mfma_f32_16x16x32_bf16 v[18:21], v[168:171], v[216:219], v[18:21]
	v_mfma_f32_16x16x32_bf16 v[22:25], v[160:163], v[216:219], v[22:25]
	v_mfma_f32_16x16x32_bf16 v[46:49], v[172:175], v[188:191], v[46:49]
	v_mfma_f32_16x16x32_bf16 v[42:45], v[180:183], v[188:191], v[42:45]
	v_mfma_f32_16x16x32_bf16 v[34:37], v[180:183], v[196:199], v[34:37]
	v_mfma_f32_16x16x32_bf16 v[38:41], v[172:175], v[196:199], v[38:41]
	v_mfma_f32_16x16x32_bf16 v[14:17], v[172:175], v[204:207], v[14:17]
	v_mfma_f32_16x16x32_bf16 v[10:13], v[180:183], v[204:207], v[10:13]
	v_mfma_f32_16x16x32_bf16 v[2:5], v[180:183], v[212:215], v[2:5]
	v_mfma_f32_16x16x32_bf16 v[6:9], v[172:175], v[212:215], v[6:9]
	v_mfma_f32_16x16x32_bf16 v[46:49], v[176:179], v[192:195], v[46:49]
	v_mfma_f32_16x16x32_bf16 v[42:45], v[184:187], v[192:195], v[42:45]
	v_mfma_f32_16x16x32_bf16 v[34:37], v[184:187], v[200:203], v[34:37]
	v_mfma_f32_16x16x32_bf16 v[38:41], v[176:179], v[200:203], v[38:41]
	v_mfma_f32_16x16x32_bf16 v[14:17], v[176:179], v[208:211], v[14:17]
	v_mfma_f32_16x16x32_bf16 v[10:13], v[184:187], v[208:211], v[10:13]
	v_mfma_f32_16x16x32_bf16 v[2:5], v[184:187], v[216:219], v[2:5]
	v_mfma_f32_16x16x32_bf16 v[6:9], v[176:179], v[216:219], v[6:9]
	s_barrier
	s_setprio 0
	s_add_i32 s54, s54, 2
	s_add_u32 s26, s26, 0x100
	s_addc_u32 s27, s27, 0
	s_add_u32 s52, s52, 0x100
	s_addc_u32 s53, s53, 0
.LBB0_788:
	ds_read_b128 v[156:159], v153
	ds_read_b128 v[160:163], v153 offset:1024
	ds_read_b128 v[164:167], v153 offset:2048
	ds_read_b128 v[168:171], v153 offset:3072
	ds_read_b128 v[172:175], v154
	ds_read_b128 v[176:179], v154 offset:1024
	ds_read_b128 v[180:183], v154 offset:2048
	ds_read_b128 v[184:187], v154 offset:3072
	s_add_u32 s36, s26, 0xfff00080
	s_addc_u32 s37, s27, -1
	s_cmp_eq_u32 s54, 60
	s_cselect_b32 s39, s19, s37
	s_cselect_b32 s38, s50, s36
	s_cselect_b32 s37, s17, s53
	s_cselect_b32 s36, s51, s52
	v_lshl_add_u64 v[148:149], s[26:27], 0, v[140:141]
	s_add_i32 m0, s25, 0xc000
	ds_read_b128 v[188:191], v155
	ds_read_b128 v[192:195], v155 offset:1024
	ds_read_b128 v[196:199], v155 offset:2048
	ds_read_b128 v[200:203], v155 offset:3072
	ds_read_b128 v[204:207], v155 offset:4096
	ds_read_b128 v[208:211], v155 offset:5120
	ds_read_b128 v[212:215], v155 offset:6144
	ds_read_b128 v[216:219], v155 offset:7168
	global_load_lds_dwordx4 v[148:149], off
	v_lshl_add_u64 v[148:149], s[26:27], 0, v[142:143]
	s_add_i32 m0, s25, 0xe000
	s_nop 0
	global_load_lds_dwordx4 v[148:149], off
	s_waitcnt vmcnt(8)
	s_waitcnt lgkmcnt(0)
	s_setprio 1
	s_barrier
	v_mfma_f32_16x16x32_bf16 v[126:129], v[156:159], v[188:191], v[126:129]
	v_mfma_f32_16x16x32_bf16 v[122:125], v[164:167], v[188:191], v[122:125]
	v_mfma_f32_16x16x32_bf16 v[114:117], v[164:167], v[196:199], v[114:117]
	v_mfma_f32_16x16x32_bf16 v[118:121], v[156:159], v[196:199], v[118:121]
	v_mfma_f32_16x16x32_bf16 v[94:97], v[156:159], v[204:207], v[94:97]
	v_mfma_f32_16x16x32_bf16 v[90:93], v[164:167], v[204:207], v[90:93]
	v_mfma_f32_16x16x32_bf16 v[82:85], v[164:167], v[212:215], v[82:85]
	v_mfma_f32_16x16x32_bf16 v[86:89], v[156:159], v[212:215], v[86:89]
	v_mfma_f32_16x16x32_bf16 v[126:129], v[160:163], v[192:195], v[126:129]
	v_mfma_f32_16x16x32_bf16 v[122:125], v[168:171], v[192:195], v[122:125]
	v_mfma_f32_16x16x32_bf16 v[114:117], v[168:171], v[200:203], v[114:117]
	v_mfma_f32_16x16x32_bf16 v[118:121], v[160:163], v[200:203], v[118:121]
	v_mfma_f32_16x16x32_bf16 v[94:97], v[160:163], v[208:211], v[94:97]
	v_mfma_f32_16x16x32_bf16 v[90:93], v[168:171], v[208:211], v[90:93]
	v_mfma_f32_16x16x32_bf16 v[82:85], v[168:171], v[216:219], v[82:85]
	v_mfma_f32_16x16x32_bf16 v[86:89], v[160:163], v[216:219], v[86:89]
	v_mfma_f32_16x16x32_bf16 v[110:113], v[172:175], v[188:191], v[110:113]
	v_mfma_f32_16x16x32_bf16 v[106:109], v[180:183], v[188:191], v[106:109]
	v_mfma_f32_16x16x32_bf16 v[98:101], v[180:183], v[196:199], v[98:101]
	v_mfma_f32_16x16x32_bf16 v[102:105], v[172:175], v[196:199], v[102:105]
	v_mfma_f32_16x16x32_bf16 v[78:81], v[172:175], v[204:207], v[78:81]
	v_mfma_f32_16x16x32_bf16 v[74:77], v[180:183], v[204:207], v[74:77]
	v_mfma_f32_16x16x32_bf16 v[66:69], v[180:183], v[212:215], v[66:69]
	v_mfma_f32_16x16x32_bf16 v[70:73], v[172:175], v[212:215], v[70:73]
	v_mfma_f32_16x16x32_bf16 v[110:113], v[176:179], v[192:195], v[110:113]
	v_mfma_f32_16x16x32_bf16 v[106:109], v[184:187], v[192:195], v[106:109]
	v_mfma_f32_16x16x32_bf16 v[98:101], v[184:187], v[200:203], v[98:101]
	v_mfma_f32_16x16x32_bf16 v[102:105], v[176:179], v[200:203], v[102:105]
	v_mfma_f32_16x16x32_bf16 v[78:81], v[176:179], v[208:211], v[78:81]
	v_mfma_f32_16x16x32_bf16 v[74:77], v[184:187], v[208:211], v[74:77]
	v_mfma_f32_16x16x32_bf16 v[66:69], v[184:187], v[216:219], v[66:69]
	v_mfma_f32_16x16x32_bf16 v[70:73], v[176:179], v[216:219], v[70:73]
	s_barrier
	s_setprio 0
	s_add_i32 s55, s44, s13
	v_lshl_add_u64 v[148:149], s[36:37], 0, v[134:135]
	s_mov_b32 m0, s55
	ds_read_b128 v[188:191], v155 offset:16384
	ds_read_b128 v[192:195], v155 offset:17408
	ds_read_b128 v[196:199], v155 offset:18432
	ds_read_b128 v[200:203], v155 offset:19456
	ds_read_b128 v[204:207], v155 offset:20480
	ds_read_b128 v[208:211], v155 offset:21504
	ds_read_b128 v[212:215], v155 offset:22528
	ds_read_b128 v[216:219], v155 offset:23552
	global_load_lds_dwordx4 v[148:149], off
	s_add_i32 m0, s55, 0x2000
	s_add_u32 s56, s36, 0x100000
	v_lshl_add_u64 v[220:221], s[36:37], 0, v[130:131]
	s_addc_u32 s57, s37, 0
	s_add_i32 s55, s45, s13
	global_load_lds_dwordx4 v[220:221], off
	v_lshl_add_u64 v[224:225], s[56:57], 0, v[134:135]
	s_mov_b32 m0, s55
	v_lshl_add_u64 v[226:227], s[38:39], 0, v[132:133]
	global_load_lds_dwordx4 v[224:225], off
	v_lshl_add_u64 v[224:225], s[56:57], 0, v[130:131]
	s_add_i32 m0, s55, 0x2000
	s_nop 0
	global_load_lds_dwordx4 v[224:225], off
	v_lshl_add_u64 v[224:225], s[38:39], 0, v[136:137]
	s_mov_b32 m0, s25
	s_nop 0
	global_load_lds_dwordx4 v[224:225], off
	s_mov_b32 m0, s31
	s_nop 0
	global_load_lds_dwordx4 v[226:227], off
	s_waitcnt vmcnt(8)
	s_waitcnt lgkmcnt(0)
	s_setprio 1
	s_barrier
	v_mfma_f32_16x16x32_bf16 v[62:65], v[156:159], v[188:191], v[62:65]
	v_mfma_f32_16x16x32_bf16 v[58:61], v[164:167], v[188:191], v[58:61]
	v_mfma_f32_16x16x32_bf16 v[50:53], v[164:167], v[196:199], v[50:53]
	v_mfma_f32_16x16x32_bf16 v[54:57], v[156:159], v[196:199], v[54:57]
	v_mfma_f32_16x16x32_bf16 v[30:33], v[156:159], v[204:207], v[30:33]
	v_mfma_f32_16x16x32_bf16 v[26:29], v[164:167], v[204:207], v[26:29]
	v_mfma_f32_16x16x32_bf16 v[18:21], v[164:167], v[212:215], v[18:21]
	v_mfma_f32_16x16x32_bf16 v[22:25], v[156:159], v[212:215], v[22:25]
	v_mfma_f32_16x16x32_bf16 v[62:65], v[160:163], v[192:195], v[62:65]
	v_mfma_f32_16x16x32_bf16 v[58:61], v[168:171], v[192:195], v[58:61]
	v_mfma_f32_16x16x32_bf16 v[50:53], v[168:171], v[200:203], v[50:53]
	v_mfma_f32_16x16x32_bf16 v[54:57], v[160:163], v[200:203], v[54:57]
	v_mfma_f32_16x16x32_bf16 v[30:33], v[160:163], v[208:211], v[30:33]
	v_mfma_f32_16x16x32_bf16 v[26:29], v[168:171], v[208:211], v[26:29]
	v_mfma_f32_16x16x32_bf16 v[18:21], v[168:171], v[216:219], v[18:21]
	v_mfma_f32_16x16x32_bf16 v[22:25], v[160:163], v[216:219], v[22:25]
	v_mfma_f32_16x16x32_bf16 v[46:49], v[172:175], v[188:191], v[46:49]
	v_mfma_f32_16x16x32_bf16 v[42:45], v[180:183], v[188:191], v[42:45]
	v_mfma_f32_16x16x32_bf16 v[34:37], v[180:183], v[196:199], v[34:37]
	v_mfma_f32_16x16x32_bf16 v[38:41], v[172:175], v[196:199], v[38:41]
	v_mfma_f32_16x16x32_bf16 v[14:17], v[172:175], v[204:207], v[14:17]
	v_mfma_f32_16x16x32_bf16 v[10:13], v[180:183], v[204:207], v[10:13]
	v_mfma_f32_16x16x32_bf16 v[2:5], v[180:183], v[212:215], v[2:5]
	v_mfma_f32_16x16x32_bf16 v[6:9], v[172:175], v[212:215], v[6:9]
	v_mfma_f32_16x16x32_bf16 v[46:49], v[176:179], v[192:195], v[46:49]
	v_mfma_f32_16x16x32_bf16 v[42:45], v[184:187], v[192:195], v[42:45]
	v_mfma_f32_16x16x32_bf16 v[34:37], v[184:187], v[200:203], v[34:37]
	v_mfma_f32_16x16x32_bf16 v[38:41], v[176:179], v[200:203], v[38:41]
	v_mfma_f32_16x16x32_bf16 v[14:17], v[176:179], v[208:211], v[14:17]
	v_mfma_f32_16x16x32_bf16 v[10:13], v[184:187], v[208:211], v[10:13]
	v_mfma_f32_16x16x32_bf16 v[2:5], v[184:187], v[216:219], v[2:5]
	v_mfma_f32_16x16x32_bf16 v[6:9], v[176:179], v[216:219], v[6:9]
	s_barrier
	s_setprio 0
	s_add_i32 s55, 0, 0x18000
	s_add_i32 s56, 0, 0x1c000
	v_add_u32_e32 v168, s55, v151
	v_add_u32_e32 v184, s56, v151
	ds_read_b128 v[156:159], v168
	ds_read_b128 v[160:163], v168 offset:1024
	ds_read_b128 v[164:167], v168 offset:2048
	ds_read_b128 v[168:171], v168 offset:3072
	ds_read_b128 v[172:175], v184
	ds_read_b128 v[176:179], v184 offset:1024
	ds_read_b128 v[180:183], v184 offset:2048
	ds_read_b128 v[184:187], v184 offset:3072
	s_add_u32 s38, s38, 0x100000
	s_addc_u32 s39, s39, 0
	s_mov_b32 m0, s34
	v_lshl_add_u64 v[228:229], s[38:39], 0, v[136:137]
	ds_read_b128 v[188:191], v155 offset:32768
	ds_read_b128 v[192:195], v155 offset:33792
	ds_read_b128 v[196:199], v155 offset:34816
	ds_read_b128 v[200:203], v155 offset:35840
	ds_read_b128 v[204:207], v155 offset:36864
	ds_read_b128 v[208:211], v155 offset:37888
	ds_read_b128 v[212:215], v155 offset:38912
	ds_read_b128 v[216:219], v155 offset:39936
	global_load_lds_dwordx4 v[228:229], off
	v_lshl_add_u64 v[228:229], s[38:39], 0, v[132:133]
	s_mov_b32 m0, s35
	s_nop 0
	global_load_lds_dwordx4 v[228:229], off
	s_waitcnt vmcnt(8)
	s_waitcnt lgkmcnt(0)
	s_setprio 1
	s_barrier
	v_mfma_f32_16x16x32_bf16 v[126:129], v[156:159], v[188:191], v[126:129]
	v_mfma_f32_16x16x32_bf16 v[122:125], v[164:167], v[188:191], v[122:125]
	v_mfma_f32_16x16x32_bf16 v[114:117], v[164:167], v[196:199], v[114:117]
	v_mfma_f32_16x16x32_bf16 v[118:121], v[156:159], v[196:199], v[118:121]
	v_mfma_f32_16x16x32_bf16 v[94:97], v[156:159], v[204:207], v[94:97]
	v_mfma_f32_16x16x32_bf16 v[90:93], v[164:167], v[204:207], v[90:93]
	v_mfma_f32_16x16x32_bf16 v[82:85], v[164:167], v[212:215], v[82:85]
	v_mfma_f32_16x16x32_bf16 v[86:89], v[156:159], v[212:215], v[86:89]
	v_mfma_f32_16x16x32_bf16 v[126:129], v[160:163], v[192:195], v[126:129]
	v_mfma_f32_16x16x32_bf16 v[122:125], v[168:171], v[192:195], v[122:125]
	v_mfma_f32_16x16x32_bf16 v[114:117], v[168:171], v[200:203], v[114:117]
	v_mfma_f32_16x16x32_bf16 v[118:121], v[160:163], v[200:203], v[118:121]
	v_mfma_f32_16x16x32_bf16 v[94:97], v[160:163], v[208:211], v[94:97]
	v_mfma_f32_16x16x32_bf16 v[90:93], v[168:171], v[208:211], v[90:93]
	v_mfma_f32_16x16x32_bf16 v[82:85], v[168:171], v[216:219], v[82:85]
	v_mfma_f32_16x16x32_bf16 v[86:89], v[160:163], v[216:219], v[86:89]
	v_mfma_f32_16x16x32_bf16 v[110:113], v[172:175], v[188:191], v[110:113]
	v_mfma_f32_16x16x32_bf16 v[106:109], v[180:183], v[188:191], v[106:109]
	v_mfma_f32_16x16x32_bf16 v[98:101], v[180:183], v[196:199], v[98:101]
	v_mfma_f32_16x16x32_bf16 v[102:105], v[172:175], v[196:199], v[102:105]
	v_mfma_f32_16x16x32_bf16 v[78:81], v[172:175], v[204:207], v[78:81]
	v_mfma_f32_16x16x32_bf16 v[74:77], v[180:183], v[204:207], v[74:77]
	v_mfma_f32_16x16x32_bf16 v[66:69], v[180:183], v[212:215], v[66:69]
	v_mfma_f32_16x16x32_bf16 v[70:73], v[172:175], v[212:215], v[70:73]
	v_mfma_f32_16x16x32_bf16 v[110:113], v[176:179], v[192:195], v[110:113]
	v_mfma_f32_16x16x32_bf16 v[106:109], v[184:187], v[192:195], v[106:109]
	v_mfma_f32_16x16x32_bf16 v[98:101], v[184:187], v[200:203], v[98:101]
	v_mfma_f32_16x16x32_bf16 v[102:105], v[176:179], v[200:203], v[102:105]
	v_mfma_f32_16x16x32_bf16 v[78:81], v[176:179], v[208:211], v[78:81]
	v_mfma_f32_16x16x32_bf16 v[74:77], v[184:187], v[208:211], v[74:77]
	v_mfma_f32_16x16x32_bf16 v[66:69], v[184:187], v[216:219], v[66:69]
	v_mfma_f32_16x16x32_bf16 v[70:73], v[176:179], v[216:219], v[70:73]
	s_barrier
	s_setprio 0
	s_add_i32 s38, s55, s13
	v_lshl_add_u64 v[148:149], v[148:149], 0, s[6:7]
	s_mov_b32 m0, s38
	ds_read_b128 v[188:191], v155 offset:49152
	ds_read_b128 v[192:195], v155 offset:50176
	ds_read_b128 v[196:199], v155 offset:51200
	ds_read_b128 v[200:203], v155 offset:52224
	ds_read_b128 v[204:207], v155 offset:53248
	ds_read_b128 v[208:211], v155 offset:54272
	ds_read_b128 v[212:215], v155 offset:55296
	ds_read_b128 v[216:219], v155 offset:56320
	global_load_lds_dwordx4 v[148:149], off
	s_add_i32 m0, s38, 0x2000
	s_add_u32 s36, s36, 0x100080
	v_lshl_add_u64 v[148:149], v[220:221], 0, s[6:7]
	s_addc_u32 s37, s37, 0
	s_add_i32 s38, s56, s13
	global_load_lds_dwordx4 v[148:149], off
	v_lshl_add_u64 v[148:149], s[36:37], 0, v[134:135]
	s_mov_b32 m0, s38
	s_nop 0
	global_load_lds_dwordx4 v[148:149], off
	v_lshl_add_u64 v[148:149], s[36:37], 0, v[130:131]
	s_add_i32 m0, s38, 0x2000
	s_nop 0
	global_load_lds_dwordx4 v[148:149], off
	v_lshl_add_u64 v[148:149], v[224:225], 0, s[6:7]
	s_mov_b32 m0, s41
	s_nop 0
	global_load_lds_dwordx4 v[148:149], off
	v_lshl_add_u64 v[148:149], v[226:227], 0, s[6:7]
	s_mov_b32 m0, s42
	s_nop 0
	global_load_lds_dwordx4 v[148:149], off
	s_waitcnt vmcnt(8)
	s_waitcnt lgkmcnt(0)
	s_setprio 1
	s_barrier
	v_mfma_f32_16x16x32_bf16 v[62:65], v[156:159], v[188:191], v[62:65]
	v_mfma_f32_16x16x32_bf16 v[58:61], v[164:167], v[188:191], v[58:61]
	v_mfma_f32_16x16x32_bf16 v[50:53], v[164:167], v[196:199], v[50:53]
	v_mfma_f32_16x16x32_bf16 v[54:57], v[156:159], v[196:199], v[54:57]
	v_mfma_f32_16x16x32_bf16 v[30:33], v[156:159], v[204:207], v[30:33]
	v_mfma_f32_16x16x32_bf16 v[26:29], v[164:167], v[204:207], v[26:29]
	v_mfma_f32_16x16x32_bf16 v[18:21], v[164:167], v[212:215], v[18:21]
	v_mfma_f32_16x16x32_bf16 v[22:25], v[156:159], v[212:215], v[22:25]
	v_mfma_f32_16x16x32_bf16 v[62:65], v[160:163], v[192:195], v[62:65]
	v_mfma_f32_16x16x32_bf16 v[58:61], v[168:171], v[192:195], v[58:61]
	v_mfma_f32_16x16x32_bf16 v[50:53], v[168:171], v[200:203], v[50:53]
	v_mfma_f32_16x16x32_bf16 v[54:57], v[160:163], v[200:203], v[54:57]
	v_mfma_f32_16x16x32_bf16 v[30:33], v[160:163], v[208:211], v[30:33]
	v_mfma_f32_16x16x32_bf16 v[26:29], v[168:171], v[208:211], v[26:29]
	v_mfma_f32_16x16x32_bf16 v[18:21], v[168:171], v[216:219], v[18:21]
	v_mfma_f32_16x16x32_bf16 v[22:25], v[160:163], v[216:219], v[22:25]
	v_mfma_f32_16x16x32_bf16 v[46:49], v[172:175], v[188:191], v[46:49]
	v_mfma_f32_16x16x32_bf16 v[42:45], v[180:183], v[188:191], v[42:45]
	v_mfma_f32_16x16x32_bf16 v[34:37], v[180:183], v[196:199], v[34:37]
	v_mfma_f32_16x16x32_bf16 v[38:41], v[172:175], v[196:199], v[38:41]
	v_mfma_f32_16x16x32_bf16 v[14:17], v[172:175], v[204:207], v[14:17]
	v_mfma_f32_16x16x32_bf16 v[10:13], v[180:183], v[204:207], v[10:13]
	v_mfma_f32_16x16x32_bf16 v[2:5], v[180:183], v[212:215], v[2:5]
	v_mfma_f32_16x16x32_bf16 v[6:9], v[172:175], v[212:215], v[6:9]
	v_mfma_f32_16x16x32_bf16 v[46:49], v[176:179], v[192:195], v[46:49]
	v_mfma_f32_16x16x32_bf16 v[42:45], v[184:187], v[192:195], v[42:45]
	v_mfma_f32_16x16x32_bf16 v[34:37], v[184:187], v[200:203], v[34:37]
	v_mfma_f32_16x16x32_bf16 v[38:41], v[176:179], v[200:203], v[38:41]
	v_mfma_f32_16x16x32_bf16 v[14:17], v[176:179], v[208:211], v[14:17]
	v_mfma_f32_16x16x32_bf16 v[10:13], v[184:187], v[208:211], v[10:13]
	v_mfma_f32_16x16x32_bf16 v[2:5], v[184:187], v[216:219], v[2:5]
	v_mfma_f32_16x16x32_bf16 v[6:9], v[176:179], v[216:219], v[6:9]
	s_barrier
	s_setprio 0
	s_add_i32 s54, s54, 2
	s_add_u32 s26, s26, 0x100
	s_addc_u32 s27, s27, 0
	s_add_u32 s52, s52, 0x100
	s_addc_u32 s53, s53, 0
	s_cmp_gt_u32 s54, 61
	s_cbranch_scc0 .LBB0_788
	s_and_b64 vcc, exec, s[8:9]
	s_cbranch_vccz .LBB0_791
	s_barrier

.Lpeeld:
	ds_read_b128 v[130:133], v207
	ds_read_b128 v[134:137], v207 offset:1024
	ds_read_b128 v[138:141], v207 offset:2048
	ds_read_b128 v[142:145], v207 offset:3072
	ds_read_b128 v[146:149], v208
	ds_read_b128 v[172:175], v208 offset:1024
	ds_read_b128 v[176:179], v208 offset:2048
	ds_read_b128 v[210:213], v208 offset:3072
	s_add_u32 s10, s8, 0xffd50080
	s_addc_u32 s11, s9, -1
	s_cmpk_eq_i32 s16, 0xa8
	s_cselect_b32 s13, s25, s11
	s_cselect_b32 s12, s24, s10
	s_cselect_b32 s11, s41, s15
	s_cselect_b32 s10, s40, s14
	v_lshl_add_u64 v[180:181], s[8:9], 0, v[166:167]
	s_add_i32 m0, s48, 0xc000
	ds_read_b128 v[214:217], v202
	ds_read_b128 v[218:221], v202 offset:1024
	ds_read_b128 v[224:227], v202 offset:2048
	ds_read_b128 v[228:231], v202 offset:3072
	ds_read_b128 v[232:235], v202 offset:4096
	ds_read_b128 v[236:239], v202 offset:5120
	ds_read_b128 v[240:243], v202 offset:6144
	ds_read_b128 v[244:247], v202 offset:7168
	global_load_lds_dwordx4 v[180:181], off
	v_lshl_add_u64 v[180:181], s[8:9], 0, v[168:169]
	s_add_i32 m0, s48, 0xe000
	s_nop 0
	global_load_lds_dwordx4 v[180:181], off
	s_waitcnt vmcnt(8)
	s_waitcnt lgkmcnt(0)
	s_setprio 1
	s_barrier
	v_mfma_f32_16x16x32_bf16 v[90:93], v[130:133], v[214:217], 0
	v_mfma_f32_16x16x32_bf16 v[74:77], v[138:141], v[214:217], 0
	v_mfma_f32_16x16x32_bf16 v[42:45], v[138:141], v[224:227], 0
	v_mfma_f32_16x16x32_bf16 v[46:49], v[130:133], v[224:227], 0
	v_mfma_f32_16x16x32_bf16 v[126:129], v[130:133], v[232:235], 0
	v_mfma_f32_16x16x32_bf16 v[122:125], v[138:141], v[232:235], 0
	v_mfma_f32_16x16x32_bf16 v[106:109], v[138:141], v[240:243], 0
	v_mfma_f32_16x16x32_bf16 v[110:113], v[130:133], v[240:243], 0
	v_mfma_f32_16x16x32_bf16 v[90:93], v[134:137], v[218:221], v[90:93]
	v_mfma_f32_16x16x32_bf16 v[74:77], v[142:145], v[218:221], v[74:77]
	v_mfma_f32_16x16x32_bf16 v[42:45], v[142:145], v[228:231], v[42:45]
	v_mfma_f32_16x16x32_bf16 v[46:49], v[134:137], v[228:231], v[46:49]
	v_mfma_f32_16x16x32_bf16 v[126:129], v[134:137], v[236:239], v[126:129]
	v_mfma_f32_16x16x32_bf16 v[122:125], v[142:145], v[236:239], v[122:125]
	v_mfma_f32_16x16x32_bf16 v[106:109], v[142:145], v[244:247], v[106:109]
	v_mfma_f32_16x16x32_bf16 v[110:113], v[134:137], v[244:247], v[110:113]
	v_mfma_f32_16x16x32_bf16 v[70:73], v[146:149], v[214:217], 0
	v_mfma_f32_16x16x32_bf16 v[66:69], v[176:179], v[214:217], 0
	v_mfma_f32_16x16x32_bf16 v[38:41], v[176:179], v[224:227], 0
	v_mfma_f32_16x16x32_bf16 v[34:37], v[146:149], v[224:227], 0
	v_mfma_f32_16x16x32_bf16 v[118:121], v[146:149], v[232:235], 0
	v_mfma_f32_16x16x32_bf16 v[114:117], v[176:179], v[232:235], 0
	v_mfma_f32_16x16x32_bf16 v[98:101], v[176:179], v[240:243], 0
	v_mfma_f32_16x16x32_bf16 v[102:105], v[146:149], v[240:243], 0
	v_mfma_f32_16x16x32_bf16 v[70:73], v[172:175], v[218:221], v[70:73]
	v_mfma_f32_16x16x32_bf16 v[66:69], v[210:213], v[218:221], v[66:69]
	v_mfma_f32_16x16x32_bf16 v[38:41], v[210:213], v[228:231], v[38:41]
	v_mfma_f32_16x16x32_bf16 v[34:37], v[172:175], v[228:231], v[34:37]
	v_mfma_f32_16x16x32_bf16 v[118:121], v[172:175], v[236:239], v[118:121]
	v_mfma_f32_16x16x32_bf16 v[114:117], v[210:213], v[236:239], v[114:117]
	v_mfma_f32_16x16x32_bf16 v[98:101], v[210:213], v[244:247], v[98:101]
	v_mfma_f32_16x16x32_bf16 v[102:105], v[172:175], v[244:247], v[102:105]
	s_barrier
	s_setprio 0
	s_add_i32 s17, s57, s46
	v_lshl_add_u64 v[180:181], s[10:11], 0, v[150:151]
	s_mov_b32 m0, s17
	ds_read_b128 v[214:217], v202 offset:16384
	ds_read_b128 v[218:221], v202 offset:17408
	ds_read_b128 v[224:227], v202 offset:18432
	ds_read_b128 v[228:231], v202 offset:19456
	ds_read_b128 v[232:235], v202 offset:20480
	ds_read_b128 v[236:239], v202 offset:21504
	ds_read_b128 v[240:243], v202 offset:22528
	ds_read_b128 v[244:247], v202 offset:23552
	global_load_lds_dwordx4 v[180:181], off
	s_add_i32 m0, s17, 0x2000
	s_add_u32 s18, s10, 0x2b0000
	v_lshl_add_u64 v[248:249], s[10:11], 0, v[152:153]
	s_addc_u32 s19, s11, 0
	s_add_i32 s17, s58, s46
	global_load_lds_dwordx4 v[248:249], off
	v_lshl_add_u64 v[250:251], s[18:19], 0, v[150:151]
	s_mov_b32 m0, s17
	v_lshl_add_u64 v[252:253], s[12:13], 0, v[152:153]
	global_load_lds_dwordx4 v[250:251], off
	v_lshl_add_u64 v[250:251], s[18:19], 0, v[152:153]
	s_add_i32 m0, s17, 0x2000
	s_nop 0
	global_load_lds_dwordx4 v[250:251], off
	v_lshl_add_u64 v[250:251], s[12:13], 0, v[150:151]
	s_mov_b32 m0, s48
	s_nop 0
	global_load_lds_dwordx4 v[250:251], off
	s_mov_b32 m0, s49
	s_nop 0
	global_load_lds_dwordx4 v[252:253], off
	s_waitcnt vmcnt(8)
	s_waitcnt lgkmcnt(0)
	s_setprio 1
	s_barrier
	v_mfma_f32_16x16x32_bf16 v[94:97], v[130:133], v[214:217], 0
	v_mfma_f32_16x16x32_bf16 v[86:89], v[138:141], v[214:217], 0
	v_mfma_f32_16x16x32_bf16 v[78:81], v[138:141], v[224:227], 0
	v_mfma_f32_16x16x32_bf16 v[82:85], v[130:133], v[224:227], 0
	v_mfma_f32_16x16x32_bf16 v[30:33], v[130:133], v[232:235], 0
	v_mfma_f32_16x16x32_bf16 v[26:29], v[138:141], v[232:235], 0
	v_mfma_f32_16x16x32_bf16 v[18:21], v[138:141], v[240:243], 0
	v_mfma_f32_16x16x32_bf16 v[22:25], v[130:133], v[240:243], 0
	v_mfma_f32_16x16x32_bf16 v[94:97], v[134:137], v[218:221], v[94:97]
	v_mfma_f32_16x16x32_bf16 v[86:89], v[142:145], v[218:221], v[86:89]
	v_mfma_f32_16x16x32_bf16 v[78:81], v[142:145], v[228:231], v[78:81]
	v_mfma_f32_16x16x32_bf16 v[82:85], v[134:137], v[228:231], v[82:85]
	v_mfma_f32_16x16x32_bf16 v[30:33], v[134:137], v[236:239], v[30:33]
	v_mfma_f32_16x16x32_bf16 v[26:29], v[142:145], v[236:239], v[26:29]
	v_mfma_f32_16x16x32_bf16 v[18:21], v[142:145], v[244:247], v[18:21]
	v_mfma_f32_16x16x32_bf16 v[22:25], v[134:137], v[244:247], v[22:25]
	v_mfma_f32_16x16x32_bf16 v[62:65], v[146:149], v[214:217], 0
	v_mfma_f32_16x16x32_bf16 v[58:61], v[176:179], v[214:217], 0
	v_mfma_f32_16x16x32_bf16 v[50:53], v[176:179], v[224:227], 0
	v_mfma_f32_16x16x32_bf16 v[54:57], v[146:149], v[224:227], 0
	v_mfma_f32_16x16x32_bf16 v[14:17], v[146:149], v[232:235], 0
	v_mfma_f32_16x16x32_bf16 v[6:9], v[176:179], v[232:235], 0
	v_mfma_f32_16x16x32_bf16 v[2:5], v[176:179], v[240:243], 0
	v_mfma_f32_16x16x32_bf16 v[10:13], v[146:149], v[240:243], 0
	v_mfma_f32_16x16x32_bf16 v[62:65], v[172:175], v[218:221], v[62:65]
	v_mfma_f32_16x16x32_bf16 v[58:61], v[210:213], v[218:221], v[58:61]
	v_mfma_f32_16x16x32_bf16 v[50:53], v[210:213], v[228:231], v[50:53]
	v_mfma_f32_16x16x32_bf16 v[54:57], v[172:175], v[228:231], v[54:57]
	v_mfma_f32_16x16x32_bf16 v[14:17], v[172:175], v[236:239], v[14:17]
	v_mfma_f32_16x16x32_bf16 v[6:9], v[210:213], v[236:239], v[6:9]
	v_mfma_f32_16x16x32_bf16 v[2:5], v[210:213], v[244:247], v[2:5]
	v_mfma_f32_16x16x32_bf16 v[10:13], v[172:175], v[244:247], v[10:13]
	s_barrier
	s_setprio 0
	s_add_i32 s17, 0, 0x18000
	s_add_i32 s18, 0, 0x1c000
	v_add_u32_e32 v142, s17, v182
	v_add_u32_e32 v154, s18, v182
	ds_read_b128 v[130:133], v142
	ds_read_b128 v[134:137], v142 offset:1024
	ds_read_b128 v[138:141], v142 offset:2048
	ds_read_b128 v[142:145], v142 offset:3072
	ds_read_b128 v[146:149], v154
	ds_read_b128 v[172:175], v154 offset:1024
	ds_read_b128 v[176:179], v154 offset:2048
	ds_read_b128 v[210:213], v154 offset:3072
	s_add_u32 s12, s12, 0x2b0000
	s_addc_u32 s13, s13, 0
	s_mov_b32 m0, s50
	v_lshl_add_u64 v[188:189], s[12:13], 0, v[150:151]
	ds_read_b128 v[214:217], v202 offset:32768
	ds_read_b128 v[218:221], v202 offset:33792
	ds_read_b128 v[224:227], v202 offset:34816
	ds_read_b128 v[228:231], v202 offset:35840
	ds_read_b128 v[232:235], v202 offset:36864
	ds_read_b128 v[236:239], v202 offset:37888
	ds_read_b128 v[240:243], v202 offset:38912
	ds_read_b128 v[244:247], v202 offset:39936
	global_load_lds_dwordx4 v[188:189], off
	v_lshl_add_u64 v[188:189], s[12:13], 0, v[152:153]
	s_mov_b32 m0, s51
	s_nop 0
	global_load_lds_dwordx4 v[188:189], off
	s_waitcnt vmcnt(8)
	s_waitcnt lgkmcnt(0)
	s_setprio 1
	s_barrier
	v_mfma_f32_16x16x32_bf16 v[90:93], v[130:133], v[214:217], v[90:93]
	v_mfma_f32_16x16x32_bf16 v[74:77], v[138:141], v[214:217], v[74:77]
	v_mfma_f32_16x16x32_bf16 v[42:45], v[138:141], v[224:227], v[42:45]
	v_mfma_f32_16x16x32_bf16 v[46:49], v[130:133], v[224:227], v[46:49]
	v_mfma_f32_16x16x32_bf16 v[126:129], v[130:133], v[232:235], v[126:129]
	v_mfma_f32_16x16x32_bf16 v[122:125], v[138:141], v[232:235], v[122:125]
	v_mfma_f32_16x16x32_bf16 v[106:109], v[138:141], v[240:243], v[106:109]
	v_mfma_f32_16x16x32_bf16 v[110:113], v[130:133], v[240:243], v[110:113]
	v_mfma_f32_16x16x32_bf16 v[90:93], v[134:137], v[218:221], v[90:93]
	v_mfma_f32_16x16x32_bf16 v[74:77], v[142:145], v[218:221], v[74:77]
	v_mfma_f32_16x16x32_bf16 v[42:45], v[142:145], v[228:231], v[42:45]
	v_mfma_f32_16x16x32_bf16 v[46:49], v[134:137], v[228:231], v[46:49]
	v_mfma_f32_16x16x32_bf16 v[126:129], v[134:137], v[236:239], v[126:129]
	v_mfma_f32_16x16x32_bf16 v[122:125], v[142:145], v[236:239], v[122:125]
	v_mfma_f32_16x16x32_bf16 v[106:109], v[142:145], v[244:247], v[106:109]
	v_mfma_f32_16x16x32_bf16 v[110:113], v[134:137], v[244:247], v[110:113]
	v_mfma_f32_16x16x32_bf16 v[70:73], v[146:149], v[214:217], v[70:73]
	v_mfma_f32_16x16x32_bf16 v[66:69], v[176:179], v[214:217], v[66:69]
	v_mfma_f32_16x16x32_bf16 v[38:41], v[176:179], v[224:227], v[38:41]
	v_mfma_f32_16x16x32_bf16 v[34:37], v[146:149], v[224:227], v[34:37]
	v_mfma_f32_16x16x32_bf16 v[118:121], v[146:149], v[232:235], v[118:121]
	v_mfma_f32_16x16x32_bf16 v[114:117], v[176:179], v[232:235], v[114:117]
	v_mfma_f32_16x16x32_bf16 v[98:101], v[176:179], v[240:243], v[98:101]
	v_mfma_f32_16x16x32_bf16 v[102:105], v[146:149], v[240:243], v[102:105]
	v_mfma_f32_16x16x32_bf16 v[70:73], v[172:175], v[218:221], v[70:73]
	v_mfma_f32_16x16x32_bf16 v[66:69], v[210:213], v[218:221], v[66:69]
	v_mfma_f32_16x16x32_bf16 v[38:41], v[210:213], v[228:231], v[38:41]
	v_mfma_f32_16x16x32_bf16 v[34:37], v[172:175], v[228:231], v[34:37]
	v_mfma_f32_16x16x32_bf16 v[118:121], v[172:175], v[236:239], v[118:121]
	v_mfma_f32_16x16x32_bf16 v[114:117], v[210:213], v[236:239], v[114:117]
	v_mfma_f32_16x16x32_bf16 v[98:101], v[210:213], v[244:247], v[98:101]
	v_mfma_f32_16x16x32_bf16 v[102:105], v[172:175], v[244:247], v[102:105]
	s_barrier
	s_setprio 0
	s_add_i32 s12, s17, s46
	v_lshl_add_u64 v[180:181], v[180:181], 0, s[30:31]
	s_mov_b32 m0, s12
	ds_read_b128 v[214:217], v202 offset:49152
	ds_read_b128 v[218:221], v202 offset:50176
	ds_read_b128 v[224:227], v202 offset:51200
	ds_read_b128 v[228:231], v202 offset:52224
	ds_read_b128 v[232:235], v202 offset:53248
	ds_read_b128 v[236:239], v202 offset:54272
	ds_read_b128 v[240:243], v202 offset:55296
	ds_read_b128 v[244:247], v202 offset:56320
	global_load_lds_dwordx4 v[180:181], off
	s_add_i32 m0, s12, 0x2000
	s_add_u32 s10, s10, 0x2b0080
	v_lshl_add_u64 v[180:181], v[248:249], 0, s[30:31]
	s_addc_u32 s11, s11, 0
	s_add_i32 s12, s18, s46
	global_load_lds_dwordx4 v[180:181], off
	v_lshl_add_u64 v[180:181], s[10:11], 0, v[150:151]
	s_mov_b32 m0, s12
	s_nop 0
	global_load_lds_dwordx4 v[180:181], off
	v_lshl_add_u64 v[180:181], s[10:11], 0, v[152:153]
	s_add_i32 m0, s12, 0x2000
	s_nop 0
	global_load_lds_dwordx4 v[180:181], off
	v_lshl_add_u64 v[180:181], v[250:251], 0, s[30:31]
	s_mov_b32 m0, s52
	s_nop 0
	global_load_lds_dwordx4 v[180:181], off
	v_lshl_add_u64 v[180:181], v[252:253], 0, s[30:31]
	s_mov_b32 m0, s53
	s_nop 0
	global_load_lds_dwordx4 v[180:181], off
	s_waitcnt vmcnt(8)
	s_waitcnt lgkmcnt(0)
	s_setprio 1
	s_barrier
	v_mfma_f32_16x16x32_bf16 v[94:97], v[130:133], v[214:217], v[94:97]
	v_mfma_f32_16x16x32_bf16 v[86:89], v[138:141], v[214:217], v[86:89]
	v_mfma_f32_16x16x32_bf16 v[78:81], v[138:141], v[224:227], v[78:81]
	v_mfma_f32_16x16x32_bf16 v[82:85], v[130:133], v[224:227], v[82:85]
	v_mfma_f32_16x16x32_bf16 v[30:33], v[130:133], v[232:235], v[30:33]
	v_mfma_f32_16x16x32_bf16 v[26:29], v[138:141], v[232:235], v[26:29]
	v_mfma_f32_16x16x32_bf16 v[18:21], v[138:141], v[240:243], v[18:21]
	v_mfma_f32_16x16x32_bf16 v[22:25], v[130:133], v[240:243], v[22:25]
	v_mfma_f32_16x16x32_bf16 v[94:97], v[134:137], v[218:221], v[94:97]
	v_mfma_f32_16x16x32_bf16 v[86:89], v[142:145], v[218:221], v[86:89]
	v_mfma_f32_16x16x32_bf16 v[78:81], v[142:145], v[228:231], v[78:81]
	v_mfma_f32_16x16x32_bf16 v[82:85], v[134:137], v[228:231], v[82:85]
	v_mfma_f32_16x16x32_bf16 v[30:33], v[134:137], v[236:239], v[30:33]
	v_mfma_f32_16x16x32_bf16 v[26:29], v[142:145], v[236:239], v[26:29]
	v_mfma_f32_16x16x32_bf16 v[18:21], v[142:145], v[244:247], v[18:21]
	v_mfma_f32_16x16x32_bf16 v[22:25], v[134:137], v[244:247], v[22:25]
	v_mfma_f32_16x16x32_bf16 v[62:65], v[146:149], v[214:217], v[62:65]
	v_mfma_f32_16x16x32_bf16 v[58:61], v[176:179], v[214:217], v[58:61]
	v_mfma_f32_16x16x32_bf16 v[50:53], v[176:179], v[224:227], v[50:53]
	v_mfma_f32_16x16x32_bf16 v[54:57], v[146:149], v[224:227], v[54:57]
	v_mfma_f32_16x16x32_bf16 v[14:17], v[146:149], v[232:235], v[14:17]
	v_mfma_f32_16x16x32_bf16 v[6:9], v[176:179], v[232:235], v[6:9]
	v_mfma_f32_16x16x32_bf16 v[2:5], v[176:179], v[240:243], v[2:5]
	v_mfma_f32_16x16x32_bf16 v[10:13], v[146:149], v[240:243], v[10:13]
	v_mfma_f32_16x16x32_bf16 v[62:65], v[172:175], v[218:221], v[62:65]
	v_mfma_f32_16x16x32_bf16 v[58:61], v[210:213], v[218:221], v[58:61]
	v_mfma_f32_16x16x32_bf16 v[50:53], v[210:213], v[228:231], v[50:53]
	v_mfma_f32_16x16x32_bf16 v[54:57], v[172:175], v[228:231], v[54:57]
	v_mfma_f32_16x16x32_bf16 v[14:17], v[172:175], v[236:239], v[14:17]
	v_mfma_f32_16x16x32_bf16 v[6:9], v[210:213], v[236:239], v[6:9]
	v_mfma_f32_16x16x32_bf16 v[2:5], v[210:213], v[244:247], v[2:5]
	v_mfma_f32_16x16x32_bf16 v[10:13], v[172:175], v[244:247], v[10:13]
	s_barrier
	s_setprio 0
	s_add_i32 s16, s16, 2
	s_add_u32 s8, s8, 0x100
	s_addc_u32 s9, s9, 0
	s_add_u32 s14, s14, 0x100
	s_addc_u32 s15, s15, 0
.LBB0_1040:
	ds_read_b128 v[130:133], v207
	ds_read_b128 v[134:137], v207 offset:1024
	ds_read_b128 v[138:141], v207 offset:2048
	ds_read_b128 v[142:145], v207 offset:3072
	ds_read_b128 v[146:149], v208
	ds_read_b128 v[172:175], v208 offset:1024
	ds_read_b128 v[176:179], v208 offset:2048
	ds_read_b128 v[210:213], v208 offset:3072
	s_add_u32 s10, s8, 0xffd50080
	s_addc_u32 s11, s9, -1
	s_cmpk_eq_i32 s16, 0xa8
	s_cselect_b32 s13, s25, s11
	s_cselect_b32 s12, s24, s10
	s_cselect_b32 s11, s41, s15
	s_cselect_b32 s10, s40, s14
	v_lshl_add_u64 v[180:181], s[8:9], 0, v[166:167]
	s_add_i32 m0, s48, 0xc000
	ds_read_b128 v[214:217], v202
	ds_read_b128 v[218:221], v202 offset:1024
	ds_read_b128 v[224:227], v202 offset:2048
	ds_read_b128 v[228:231], v202 offset:3072
	ds_read_b128 v[232:235], v202 offset:4096
	ds_read_b128 v[236:239], v202 offset:5120
	ds_read_b128 v[240:243], v202 offset:6144
	ds_read_b128 v[244:247], v202 offset:7168
	global_load_lds_dwordx4 v[180:181], off
	v_lshl_add_u64 v[180:181], s[8:9], 0, v[168:169]
	s_add_i32 m0, s48, 0xe000
	s_nop 0
	global_load_lds_dwordx4 v[180:181], off
	s_waitcnt vmcnt(8)
	s_waitcnt lgkmcnt(0)
	s_setprio 1
	s_barrier
	v_mfma_f32_16x16x32_bf16 v[90:93], v[130:133], v[214:217], v[90:93]
	v_mfma_f32_16x16x32_bf16 v[74:77], v[138:141], v[214:217], v[74:77]
	v_mfma_f32_16x16x32_bf16 v[42:45], v[138:141], v[224:227], v[42:45]
	v_mfma_f32_16x16x32_bf16 v[46:49], v[130:133], v[224:227], v[46:49]
	v_mfma_f32_16x16x32_bf16 v[126:129], v[130:133], v[232:235], v[126:129]
	v_mfma_f32_16x16x32_bf16 v[122:125], v[138:141], v[232:235], v[122:125]
	v_mfma_f32_16x16x32_bf16 v[106:109], v[138:141], v[240:243], v[106:109]
	v_mfma_f32_16x16x32_bf16 v[110:113], v[130:133], v[240:243], v[110:113]
	v_mfma_f32_16x16x32_bf16 v[90:93], v[134:137], v[218:221], v[90:93]
	v_mfma_f32_16x16x32_bf16 v[74:77], v[142:145], v[218:221], v[74:77]
	v_mfma_f32_16x16x32_bf16 v[42:45], v[142:145], v[228:231], v[42:45]
	v_mfma_f32_16x16x32_bf16 v[46:49], v[134:137], v[228:231], v[46:49]
	v_mfma_f32_16x16x32_bf16 v[126:129], v[134:137], v[236:239], v[126:129]
	v_mfma_f32_16x16x32_bf16 v[122:125], v[142:145], v[236:239], v[122:125]
	v_mfma_f32_16x16x32_bf16 v[106:109], v[142:145], v[244:247], v[106:109]
	v_mfma_f32_16x16x32_bf16 v[110:113], v[134:137], v[244:247], v[110:113]
	v_mfma_f32_16x16x32_bf16 v[70:73], v[146:149], v[214:217], v[70:73]
	v_mfma_f32_16x16x32_bf16 v[66:69], v[176:179], v[214:217], v[66:69]
	v_mfma_f32_16x16x32_bf16 v[38:41], v[176:179], v[224:227], v[38:41]
	v_mfma_f32_16x16x32_bf16 v[34:37], v[146:149], v[224:227], v[34:37]
	v_mfma_f32_16x16x32_bf16 v[118:121], v[146:149], v[232:235], v[118:121]
	v_mfma_f32_16x16x32_bf16 v[114:117], v[176:179], v[232:235], v[114:117]
	v_mfma_f32_16x16x32_bf16 v[98:101], v[176:179], v[240:243], v[98:101]
	v_mfma_f32_16x16x32_bf16 v[102:105], v[146:149], v[240:243], v[102:105]
	v_mfma_f32_16x16x32_bf16 v[70:73], v[172:175], v[218:221], v[70:73]
	v_mfma_f32_16x16x32_bf16 v[66:69], v[210:213], v[218:221], v[66:69]
	v_mfma_f32_16x16x32_bf16 v[38:41], v[210:213], v[228:231], v[38:41]
	v_mfma_f32_16x16x32_bf16 v[34:37], v[172:175], v[228:231], v[34:37]
	v_mfma_f32_16x16x32_bf16 v[118:121], v[172:175], v[236:239], v[118:121]
	v_mfma_f32_16x16x32_bf16 v[114:117], v[210:213], v[236:239], v[114:117]
	v_mfma_f32_16x16x32_bf16 v[98:101], v[210:213], v[244:247], v[98:101]
	v_mfma_f32_16x16x32_bf16 v[102:105], v[172:175], v[244:247], v[102:105]
	s_barrier
	s_setprio 0
	s_add_i32 s17, s57, s46
	v_lshl_add_u64 v[180:181], s[10:11], 0, v[150:151]
	s_mov_b32 m0, s17
	ds_read_b128 v[214:217], v202 offset:16384
	ds_read_b128 v[218:221], v202 offset:17408
	ds_read_b128 v[224:227], v202 offset:18432
	ds_read_b128 v[228:231], v202 offset:19456
	ds_read_b128 v[232:235], v202 offset:20480
	ds_read_b128 v[236:239], v202 offset:21504
	ds_read_b128 v[240:243], v202 offset:22528
	ds_read_b128 v[244:247], v202 offset:23552
	global_load_lds_dwordx4 v[180:181], off
	s_add_i32 m0, s17, 0x2000
	s_add_u32 s18, s10, 0x2b0000
	v_lshl_add_u64 v[248:249], s[10:11], 0, v[152:153]
	s_addc_u32 s19, s11, 0
	s_add_i32 s17, s58, s46
	global_load_lds_dwordx4 v[248:249], off
	v_lshl_add_u64 v[250:251], s[18:19], 0, v[150:151]
	s_mov_b32 m0, s17
	v_lshl_add_u64 v[252:253], s[12:13], 0, v[152:153]
	global_load_lds_dwordx4 v[250:251], off
	v_lshl_add_u64 v[250:251], s[18:19], 0, v[152:153]
	s_add_i32 m0, s17, 0x2000
	s_nop 0
	global_load_lds_dwordx4 v[250:251], off
	v_lshl_add_u64 v[250:251], s[12:13], 0, v[150:151]
	s_mov_b32 m0, s48
	s_nop 0
	global_load_lds_dwordx4 v[250:251], off
	s_mov_b32 m0, s49
	s_nop 0
	global_load_lds_dwordx4 v[252:253], off
	s_waitcnt vmcnt(8)
	s_waitcnt lgkmcnt(0)
	s_setprio 1
	s_barrier
	v_mfma_f32_16x16x32_bf16 v[94:97], v[130:133], v[214:217], v[94:97]
	v_mfma_f32_16x16x32_bf16 v[86:89], v[138:141], v[214:217], v[86:89]
	v_mfma_f32_16x16x32_bf16 v[78:81], v[138:141], v[224:227], v[78:81]
	v_mfma_f32_16x16x32_bf16 v[82:85], v[130:133], v[224:227], v[82:85]
	v_mfma_f32_16x16x32_bf16 v[30:33], v[130:133], v[232:235], v[30:33]
	v_mfma_f32_16x16x32_bf16 v[26:29], v[138:141], v[232:235], v[26:29]
	v_mfma_f32_16x16x32_bf16 v[18:21], v[138:141], v[240:243], v[18:21]
	v_mfma_f32_16x16x32_bf16 v[22:25], v[130:133], v[240:243], v[22:25]
	v_mfma_f32_16x16x32_bf16 v[94:97], v[134:137], v[218:221], v[94:97]
	v_mfma_f32_16x16x32_bf16 v[86:89], v[142:145], v[218:221], v[86:89]
	v_mfma_f32_16x16x32_bf16 v[78:81], v[142:145], v[228:231], v[78:81]
	v_mfma_f32_16x16x32_bf16 v[82:85], v[134:137], v[228:231], v[82:85]
	v_mfma_f32_16x16x32_bf16 v[30:33], v[134:137], v[236:239], v[30:33]
	v_mfma_f32_16x16x32_bf16 v[26:29], v[142:145], v[236:239], v[26:29]
	v_mfma_f32_16x16x32_bf16 v[18:21], v[142:145], v[244:247], v[18:21]
	v_mfma_f32_16x16x32_bf16 v[22:25], v[134:137], v[244:247], v[22:25]
	v_mfma_f32_16x16x32_bf16 v[62:65], v[146:149], v[214:217], v[62:65]
	v_mfma_f32_16x16x32_bf16 v[58:61], v[176:179], v[214:217], v[58:61]
	v_mfma_f32_16x16x32_bf16 v[50:53], v[176:179], v[224:227], v[50:53]
	v_mfma_f32_16x16x32_bf16 v[54:57], v[146:149], v[224:227], v[54:57]
	v_mfma_f32_16x16x32_bf16 v[14:17], v[146:149], v[232:235], v[14:17]
	v_mfma_f32_16x16x32_bf16 v[6:9], v[176:179], v[232:235], v[6:9]
	v_mfma_f32_16x16x32_bf16 v[2:5], v[176:179], v[240:243], v[2:5]
	v_mfma_f32_16x16x32_bf16 v[10:13], v[146:149], v[240:243], v[10:13]
	v_mfma_f32_16x16x32_bf16 v[62:65], v[172:175], v[218:221], v[62:65]
	v_mfma_f32_16x16x32_bf16 v[58:61], v[210:213], v[218:221], v[58:61]
	v_mfma_f32_16x16x32_bf16 v[50:53], v[210:213], v[228:231], v[50:53]
	v_mfma_f32_16x16x32_bf16 v[54:57], v[172:175], v[228:231], v[54:57]
	v_mfma_f32_16x16x32_bf16 v[14:17], v[172:175], v[236:239], v[14:17]
	v_mfma_f32_16x16x32_bf16 v[6:9], v[210:213], v[236:239], v[6:9]
	v_mfma_f32_16x16x32_bf16 v[2:5], v[210:213], v[244:247], v[2:5]
	v_mfma_f32_16x16x32_bf16 v[10:13], v[172:175], v[244:247], v[10:13]
	s_barrier
	s_setprio 0
	s_add_i32 s17, 0, 0x18000
	s_add_i32 s18, 0, 0x1c000
	v_add_u32_e32 v142, s17, v182
	v_add_u32_e32 v154, s18, v182
	ds_read_b128 v[130:133], v142
	ds_read_b128 v[134:137], v142 offset:1024
	ds_read_b128 v[138:141], v142 offset:2048
	ds_read_b128 v[142:145], v142 offset:3072
	ds_read_b128 v[146:149], v154
	ds_read_b128 v[172:175], v154 offset:1024
	ds_read_b128 v[176:179], v154 offset:2048
	ds_read_b128 v[210:213], v154 offset:3072
	s_add_u32 s12, s12, 0x2b0000
	s_addc_u32 s13, s13, 0
	s_mov_b32 m0, s50
	v_lshl_add_u64 v[188:189], s[12:13], 0, v[150:151]
	ds_read_b128 v[214:217], v202 offset:32768
	ds_read_b128 v[218:221], v202 offset:33792
	ds_read_b128 v[224:227], v202 offset:34816
	ds_read_b128 v[228:231], v202 offset:35840
	ds_read_b128 v[232:235], v202 offset:36864
	ds_read_b128 v[236:239], v202 offset:37888
	ds_read_b128 v[240:243], v202 offset:38912
	ds_read_b128 v[244:247], v202 offset:39936
	global_load_lds_dwordx4 v[188:189], off
	v_lshl_add_u64 v[188:189], s[12:13], 0, v[152:153]
	s_mov_b32 m0, s51
	s_nop 0
	global_load_lds_dwordx4 v[188:189], off
	s_waitcnt vmcnt(8)
	s_waitcnt lgkmcnt(0)
	s_setprio 1
	s_barrier
	v_mfma_f32_16x16x32_bf16 v[90:93], v[130:133], v[214:217], v[90:93]
	v_mfma_f32_16x16x32_bf16 v[74:77], v[138:141], v[214:217], v[74:77]
	v_mfma_f32_16x16x32_bf16 v[42:45], v[138:141], v[224:227], v[42:45]
	v_mfma_f32_16x16x32_bf16 v[46:49], v[130:133], v[224:227], v[46:49]
	v_mfma_f32_16x16x32_bf16 v[126:129], v[130:133], v[232:235], v[126:129]
	v_mfma_f32_16x16x32_bf16 v[122:125], v[138:141], v[232:235], v[122:125]
	v_mfma_f32_16x16x32_bf16 v[106:109], v[138:141], v[240:243], v[106:109]
	v_mfma_f32_16x16x32_bf16 v[110:113], v[130:133], v[240:243], v[110:113]
	v_mfma_f32_16x16x32_bf16 v[90:93], v[134:137], v[218:221], v[90:93]
	v_mfma_f32_16x16x32_bf16 v[74:77], v[142:145], v[218:221], v[74:77]
	v_mfma_f32_16x16x32_bf16 v[42:45], v[142:145], v[228:231], v[42:45]
	v_mfma_f32_16x16x32_bf16 v[46:49], v[134:137], v[228:231], v[46:49]
	v_mfma_f32_16x16x32_bf16 v[126:129], v[134:137], v[236:239], v[126:129]
	v_mfma_f32_16x16x32_bf16 v[122:125], v[142:145], v[236:239], v[122:125]
	v_mfma_f32_16x16x32_bf16 v[106:109], v[142:145], v[244:247], v[106:109]
	v_mfma_f32_16x16x32_bf16 v[110:113], v[134:137], v[244:247], v[110:113]
	v_mfma_f32_16x16x32_bf16 v[70:73], v[146:149], v[214:217], v[70:73]
	v_mfma_f32_16x16x32_bf16 v[66:69], v[176:179], v[214:217], v[66:69]
	v_mfma_f32_16x16x32_bf16 v[38:41], v[176:179], v[224:227], v[38:41]
	v_mfma_f32_16x16x32_bf16 v[34:37], v[146:149], v[224:227], v[34:37]
	v_mfma_f32_16x16x32_bf16 v[118:121], v[146:149], v[232:235], v[118:121]
	v_mfma_f32_16x16x32_bf16 v[114:117], v[176:179], v[232:235], v[114:117]
	v_mfma_f32_16x16x32_bf16 v[98:101], v[176:179], v[240:243], v[98:101]
	v_mfma_f32_16x16x32_bf16 v[102:105], v[146:149], v[240:243], v[102:105]
	v_mfma_f32_16x16x32_bf16 v[70:73], v[172:175], v[218:221], v[70:73]
	v_mfma_f32_16x16x32_bf16 v[66:69], v[210:213], v[218:221], v[66:69]
	v_mfma_f32_16x16x32_bf16 v[38:41], v[210:213], v[228:231], v[38:41]
	v_mfma_f32_16x16x32_bf16 v[34:37], v[172:175], v[228:231], v[34:37]
	v_mfma_f32_16x16x32_bf16 v[118:121], v[172:175], v[236:239], v[118:121]
	v_mfma_f32_16x16x32_bf16 v[114:117], v[210:213], v[236:239], v[114:117]
	v_mfma_f32_16x16x32_bf16 v[98:101], v[210:213], v[244:247], v[98:101]
	v_mfma_f32_16x16x32_bf16 v[102:105], v[172:175], v[244:247], v[102:105]
	s_barrier
	s_setprio 0
	s_add_i32 s12, s17, s46
	v_lshl_add_u64 v[180:181], v[180:181], 0, s[30:31]
	s_mov_b32 m0, s12
	ds_read_b128 v[214:217], v202 offset:49152
	ds_read_b128 v[218:221], v202 offset:50176
	ds_read_b128 v[224:227], v202 offset:51200
	ds_read_b128 v[228:231], v202 offset:52224
	ds_read_b128 v[232:235], v202 offset:53248
	ds_read_b128 v[236:239], v202 offset:54272
	ds_read_b128 v[240:243], v202 offset:55296
	ds_read_b128 v[244:247], v202 offset:56320
	global_load_lds_dwordx4 v[180:181], off
	s_add_i32 m0, s12, 0x2000
	s_add_u32 s10, s10, 0x2b0080
	v_lshl_add_u64 v[180:181], v[248:249], 0, s[30:31]
	s_addc_u32 s11, s11, 0
	s_add_i32 s12, s18, s46
	global_load_lds_dwordx4 v[180:181], off
	v_lshl_add_u64 v[180:181], s[10:11], 0, v[150:151]
	s_mov_b32 m0, s12
	s_nop 0
	global_load_lds_dwordx4 v[180:181], off
	v_lshl_add_u64 v[180:181], s[10:11], 0, v[152:153]
	s_add_i32 m0, s12, 0x2000
	s_nop 0
	global_load_lds_dwordx4 v[180:181], off
	v_lshl_add_u64 v[180:181], v[250:251], 0, s[30:31]
	s_mov_b32 m0, s52
	s_nop 0
	global_load_lds_dwordx4 v[180:181], off
	v_lshl_add_u64 v[180:181], v[252:253], 0, s[30:31]
	s_mov_b32 m0, s53
	s_nop 0
	global_load_lds_dwordx4 v[180:181], off
	s_waitcnt vmcnt(8)
	s_waitcnt lgkmcnt(0)
	s_setprio 1
	s_barrier
	v_mfma_f32_16x16x32_bf16 v[94:97], v[130:133], v[214:217], v[94:97]
	v_mfma_f32_16x16x32_bf16 v[86:89], v[138:141], v[214:217], v[86:89]
	v_mfma_f32_16x16x32_bf16 v[78:81], v[138:141], v[224:227], v[78:81]
	v_mfma_f32_16x16x32_bf16 v[82:85], v[130:133], v[224:227], v[82:85]
	v_mfma_f32_16x16x32_bf16 v[30:33], v[130:133], v[232:235], v[30:33]
	v_mfma_f32_16x16x32_bf16 v[26:29], v[138:141], v[232:235], v[26:29]
	v_mfma_f32_16x16x32_bf16 v[18:21], v[138:141], v[240:243], v[18:21]
	v_mfma_f32_16x16x32_bf16 v[22:25], v[130:133], v[240:243], v[22:25]
	v_mfma_f32_16x16x32_bf16 v[94:97], v[134:137], v[218:221], v[94:97]
	v_mfma_f32_16x16x32_bf16 v[86:89], v[142:145], v[218:221], v[86:89]
	v_mfma_f32_16x16x32_bf16 v[78:81], v[142:145], v[228:231], v[78:81]
	v_mfma_f32_16x16x32_bf16 v[82:85], v[134:137], v[228:231], v[82:85]
	v_mfma_f32_16x16x32_bf16 v[30:33], v[134:137], v[236:239], v[30:33]
	v_mfma_f32_16x16x32_bf16 v[26:29], v[142:145], v[236:239], v[26:29]
	v_mfma_f32_16x16x32_bf16 v[18:21], v[142:145], v[244:247], v[18:21]
	v_mfma_f32_16x16x32_bf16 v[22:25], v[134:137], v[244:247], v[22:25]
	v_mfma_f32_16x16x32_bf16 v[62:65], v[146:149], v[214:217], v[62:65]
	v_mfma_f32_16x16x32_bf16 v[58:61], v[176:179], v[214:217], v[58:61]
	v_mfma_f32_16x16x32_bf16 v[50:53], v[176:179], v[224:227], v[50:53]
	v_mfma_f32_16x16x32_bf16 v[54:57], v[146:149], v[224:227], v[54:57]
	v_mfma_f32_16x16x32_bf16 v[14:17], v[146:149], v[232:235], v[14:17]
	v_mfma_f32_16x16x32_bf16 v[6:9], v[176:179], v[232:235], v[6:9]
	v_mfma_f32_16x16x32_bf16 v[2:5], v[176:179], v[240:243], v[2:5]
	v_mfma_f32_16x16x32_bf16 v[10:13], v[146:149], v[240:243], v[10:13]
	v_mfma_f32_16x16x32_bf16 v[62:65], v[172:175], v[218:221], v[62:65]
	v_mfma_f32_16x16x32_bf16 v[58:61], v[210:213], v[218:221], v[58:61]
	v_mfma_f32_16x16x32_bf16 v[50:53], v[210:213], v[228:231], v[50:53]
	v_mfma_f32_16x16x32_bf16 v[54:57], v[172:175], v[228:231], v[54:57]
	v_mfma_f32_16x16x32_bf16 v[14:17], v[172:175], v[236:239], v[14:17]
	v_mfma_f32_16x16x32_bf16 v[6:9], v[210:213], v[236:239], v[6:9]
	v_mfma_f32_16x16x32_bf16 v[2:5], v[210:213], v[244:247], v[2:5]
	v_mfma_f32_16x16x32_bf16 v[10:13], v[172:175], v[244:247], v[10:13]
	s_barrier
	s_setprio 0
	s_add_i32 s16, s16, 2
	s_add_u32 s8, s8, 0x100
	s_addc_u32 s9, s9, 0
	s_add_u32 s14, s14, 0x100
	s_addc_u32 s15, s15, 0
	s_cmpk_gt_u32 s16, 0xa9
	s_cbranch_scc0 .LBB0_1040
	s_and_b64 vcc, exec, s[34:35]
	s_cbranch_vccz .LBB0_1043
	s_barrier
